# on top of v5: serpentine MFMA order inside each 8-group (one operand register set changes per MFMA)
# baseline (speedup 1.0000x reference)
; #define PG8_STAGE(bufoff, gbase, voff) do { _Pragma("unroll") for (int _i = 0; _i < 2; ++_i) \
;         __builtin_amdgcn_global_load_lds((const unsigned*)((const char*)(gbase) + (voff)[_i]), (PG8_LAS unsigned*)(lds + (bufoff) + ldsw + _i * 8192), 16, 0, 0); } while (0)
; #define PG8_LDA(dst, b, h) do { _Pragma("unroll") for (int m = 0; m < 4; ++m) _Pragma("unroll") for (int k = 0; k < 2; ++k) dst[m][k] = *(const PG8_LAS bf16x8*)(lds + PG8_SA(b, h) + aoff + m * 2048 + k * 1024); } while (0)
; #define PG8_LDB(dst, b, h) do { _Pragma("unroll") for (int n = 0; n < 2; ++n) _Pragma("unroll") for (int k = 0; k < 2; ++k) dst[n][k] = *(const PG8_LAS bf16x8*)(lds + PG8_SB(b, h) + boff + n * 2048 + k * 1024); } while (0)
; #define PG8_MMA(ai, bj, At, Bt) do { __builtin_amdgcn_s_setprio(1); _Pragma("unroll") for (int m = 0; m < 4; ++m) _Pragma("unroll") for (int n = 0; n < 2; ++n) _Pragma("unroll") for (int k = 0; k < 2; ++k) \
;         acc[ai][bj][m][n] = __builtin_amdgcn_mfma_f32_16x16x32_bf16(Bt[n][k], At[m][k], acc[ai][bj][m][n], 0, 0, 0); __builtin_amdgcn_s_setprio(0); } while (0)
; #define PG8_WAIT_V(n) asm volatile("s_waitcnt vmcnt(" #n ")" ::: "memory")
; #define PG8_WAIT_L(n) asm volatile("s_waitcnt lgkmcnt(" #n ")" ::: "memory")
; #define PG8_BAR __builtin_amdgcn_s_barrier()
; #define PG8_SCHED __builtin_amdgcn_sched_barrier(0)
; template <class Epi, class Sched, bool ALIGN_EPI = false, bool SP2 = false>
; __device__ __forceinline__ void gemm_phase(PG8_LAS unsigned char* lds, const Gemm g, const Sched& S, const Epi& E, const int wave_id) {
;     ...
;             if constexpr (SP2) {
;             PG8_LDB(B0, 0, 0); PG8_LDB(B1, 0, 1); PG8_SCHED; PG8_LDA(At, 0, 0); PG8_STAGE(PG8_SA(1, 1), a1 + hstep, voffA);
;             PG8_WAIT_V(8); PG8_WAIT_L(0); PG8_BAR; PG8_MMA(0, 0, At, B0); PG8_MMA(0, 1, At, B1); PG8_BAR; PG8_SCHED;
;             PG8_LDA(At, 0, 1); PG8_STAGE(PG8_SB(0, 0), b2, voffB); PG8_STAGE(PG8_SB(0, 1), b2 + hstep, voffB); PG8_STAGE(PG8_SA(0, 0), a2, voffA);
;             PG8_WAIT_V(8); PG8_WAIT_L(0); PG8_BAR; PG8_MMA(1, 0, At, B0); PG8_MMA(1, 1, At, B1); PG8_BAR; PG8_SCHED;
.LBB0_174:
	s_add_u32 s42, s20, 0xfff80080
	s_addc_u32 s43, s21, -1
	s_add_i32 s76, 0, 0x10000
	s_cmp_eq_u32 s75, 28
	s_cselect_b32 s45, s15, s43
	s_cselect_b32 s44, s41, s42
	s_cselect_b32 s43, s13, s74
	s_cselect_b32 s42, s72, s73
	s_add_i32 s79, 0, 0x14000
	s_add_i32 m0, s56, 0xc000
	s_nop 0
	global_load_lds_dwordx4 v138, s[20:21]
	ds_read_b128 v[142:145], v230
	ds_read_b128 v[146:149], v230 offset:1024
	ds_read_b128 v[150:153], v230 offset:2048
	ds_read_b128 v[154:157], v230 offset:3072
	ds_read_b128 v[158:161], v230 offset:16384
	ds_read_b128 v[162:165], v230 offset:17408
	ds_read_b128 v[166:169], v230 offset:18432
	ds_read_b128 v[178:181], v230 offset:19456
	s_add_i32 m0, s56, 0xe000
	s_nop 0
	global_load_lds_dwordx4 v140, s[20:21]
	ds_read_b128 v[182:185], v175
	ds_read_b128 v[186:189], v175 offset:1024
	ds_read_b128 v[190:193], v175 offset:2048
	ds_read_b128 v[206:209], v175 offset:3072
	ds_read_b128 v[210:213], v175 offset:4096
	ds_read_b128 v[214:217], v175 offset:5120
	ds_read_b128 v[226:229], v175 offset:6144
	ds_read_b128 v[234:237], v175 offset:7168
	s_waitcnt vmcnt(8)
	s_waitcnt lgkmcnt(0)
	s_barrier
	s_setprio 1
	s_waitcnt lgkmcnt(0)
	v_mfma_f32_16x16x32_bf16 v[126:129], v[142:145], v[182:185], v[126:129]
	v_mfma_f32_16x16x32_bf16 v[118:121], v[150:153], v[182:185], v[118:121]
	v_mfma_f32_16x16x32_bf16 v[102:105], v[150:153], v[190:193], v[102:105]
	v_mfma_f32_16x16x32_bf16 v[110:113], v[142:145], v[190:193], v[110:113]
	v_mfma_f32_16x16x32_bf16 v[94:97], v[142:145], v[210:213], v[94:97]
	v_mfma_f32_16x16x32_bf16 v[86:89], v[150:153], v[210:213], v[86:89]
	v_mfma_f32_16x16x32_bf16 v[70:73], v[150:153], v[226:229], v[70:73]
	v_mfma_f32_16x16x32_bf16 v[78:81], v[142:145], v[226:229], v[78:81]
	v_mfma_f32_16x16x32_bf16 v[126:129], v[146:149], v[186:189], v[126:129]
	v_mfma_f32_16x16x32_bf16 v[118:121], v[154:157], v[186:189], v[118:121]
	v_mfma_f32_16x16x32_bf16 v[102:105], v[154:157], v[206:209], v[102:105]
	v_mfma_f32_16x16x32_bf16 v[110:113], v[146:149], v[206:209], v[110:113]
	v_mfma_f32_16x16x32_bf16 v[94:97], v[146:149], v[214:217], v[94:97]
	v_mfma_f32_16x16x32_bf16 v[86:89], v[154:157], v[214:217], v[86:89]
	v_mfma_f32_16x16x32_bf16 v[70:73], v[154:157], v[234:237], v[70:73]
	v_mfma_f32_16x16x32_bf16 v[78:81], v[146:149], v[234:237], v[78:81]
	s_setprio 0
	s_setprio 1
	v_mfma_f32_16x16x32_bf16 v[122:125], v[158:161], v[182:185], v[122:125]
	v_mfma_f32_16x16x32_bf16 v[114:117], v[166:169], v[182:185], v[114:117]
	v_mfma_f32_16x16x32_bf16 v[98:101], v[166:169], v[190:193], v[98:101]
	v_mfma_f32_16x16x32_bf16 v[106:109], v[158:161], v[190:193], v[106:109]
	v_mfma_f32_16x16x32_bf16 v[90:93], v[158:161], v[210:213], v[90:93]
	v_mfma_f32_16x16x32_bf16 v[82:85], v[166:169], v[210:213], v[82:85]
	v_mfma_f32_16x16x32_bf16 v[66:69], v[166:169], v[226:229], v[66:69]
	v_mfma_f32_16x16x32_bf16 v[74:77], v[158:161], v[226:229], v[74:77]
	v_mfma_f32_16x16x32_bf16 v[122:125], v[162:165], v[186:189], v[122:125]
	v_mfma_f32_16x16x32_bf16 v[114:117], v[178:181], v[186:189], v[114:117]
	v_mfma_f32_16x16x32_bf16 v[98:101], v[178:181], v[206:209], v[98:101]
	v_mfma_f32_16x16x32_bf16 v[106:109], v[162:165], v[206:209], v[106:109]
	v_mfma_f32_16x16x32_bf16 v[90:93], v[162:165], v[214:217], v[90:93]
	v_mfma_f32_16x16x32_bf16 v[82:85], v[178:181], v[214:217], v[82:85]
	v_mfma_f32_16x16x32_bf16 v[66:69], v[178:181], v[234:237], v[66:69]
	v_mfma_f32_16x16x32_bf16 v[74:77], v[162:165], v[234:237], v[74:77]
	s_setprio 0
	s_barrier
	s_add_i32 s76, s76, s53
	s_mov_b32 m0, s76
	s_nop 0
	global_load_lds_dwordx4 v132, s[42:43]
	ds_read_b128 v[182:185], v175 offset:16384
	ds_read_b128 v[186:189], v175 offset:17408
	s_add_i32 m0, s76, 0x2000
	s_add_u32 s76, s42, 0x80000
	s_addc_u32 s77, s43, 0
	s_add_i32 s79, s79, s53
	global_load_lds_dwordx4 v136, s[42:43]
	ds_read_b128 v[190:193], v175 offset:18432
	ds_read_b128 v[206:209], v175 offset:19456
	s_mov_b32 m0, s79
	s_nop 0
	global_load_lds_dwordx4 v132, s[76:77]
	ds_read_b128 v[210:213], v175 offset:20480
	ds_read_b128 v[214:217], v175 offset:21504
	s_add_i32 m0, s79, 0x2000
	s_nop 0
	global_load_lds_dwordx4 v136, s[76:77]
	ds_read_b128 v[226:229], v175 offset:22528
	ds_read_b128 v[234:237], v175 offset:23552
	s_mov_b32 m0, s56
	s_nop 0
	global_load_lds_dwordx4 v130, s[44:45]
	s_mov_b32 m0, s57
	s_nop 0
	global_load_lds_dwordx4 v134, s[44:45]
	s_waitcnt vmcnt(8)
	s_waitcnt lgkmcnt(0)
	s_barrier
	s_setprio 1
	s_waitcnt lgkmcnt(0)
	v_mfma_f32_16x16x32_bf16 v[62:65], v[142:145], v[182:185], v[62:65]
	v_mfma_f32_16x16x32_bf16 v[54:57], v[150:153], v[182:185], v[54:57]
	v_mfma_f32_16x16x32_bf16 v[38:41], v[150:153], v[190:193], v[38:41]
	v_mfma_f32_16x16x32_bf16 v[46:49], v[142:145], v[190:193], v[46:49]
	v_mfma_f32_16x16x32_bf16 v[30:33], v[142:145], v[210:213], v[30:33]
	v_mfma_f32_16x16x32_bf16 v[22:25], v[150:153], v[210:213], v[22:25]
	v_mfma_f32_16x16x32_bf16 v[6:9], v[150:153], v[226:229], v[6:9]
	v_mfma_f32_16x16x32_bf16 v[14:17], v[142:145], v[226:229], v[14:17]
	v_mfma_f32_16x16x32_bf16 v[62:65], v[146:149], v[186:189], v[62:65]
	v_mfma_f32_16x16x32_bf16 v[54:57], v[154:157], v[186:189], v[54:57]
	v_mfma_f32_16x16x32_bf16 v[38:41], v[154:157], v[206:209], v[38:41]
	v_mfma_f32_16x16x32_bf16 v[46:49], v[146:149], v[206:209], v[46:49]
	v_mfma_f32_16x16x32_bf16 v[30:33], v[146:149], v[214:217], v[30:33]
	v_mfma_f32_16x16x32_bf16 v[22:25], v[154:157], v[214:217], v[22:25]
	v_mfma_f32_16x16x32_bf16 v[6:9], v[154:157], v[234:237], v[6:9]
	v_mfma_f32_16x16x32_bf16 v[14:17], v[146:149], v[234:237], v[14:17]
	s_setprio 0
	s_setprio 1
	v_mfma_f32_16x16x32_bf16 v[58:61], v[158:161], v[182:185], v[58:61]
	v_mfma_f32_16x16x32_bf16 v[50:53], v[166:169], v[182:185], v[50:53]
	v_mfma_f32_16x16x32_bf16 v[34:37], v[166:169], v[190:193], v[34:37]
	v_mfma_f32_16x16x32_bf16 v[42:45], v[158:161], v[190:193], v[42:45]
	v_mfma_f32_16x16x32_bf16 v[26:29], v[158:161], v[210:213], v[26:29]
	v_mfma_f32_16x16x32_bf16 v[18:21], v[166:169], v[210:213], v[18:21]
	v_mfma_f32_16x16x32_bf16 v[2:5], v[166:169], v[226:229], v[2:5]
	v_mfma_f32_16x16x32_bf16 v[10:13], v[158:161], v[226:229], v[10:13]
	v_mfma_f32_16x16x32_bf16 v[58:61], v[162:165], v[186:189], v[58:61]
	v_mfma_f32_16x16x32_bf16 v[50:53], v[178:181], v[186:189], v[50:53]
	v_mfma_f32_16x16x32_bf16 v[34:37], v[178:181], v[206:209], v[34:37]
	v_mfma_f32_16x16x32_bf16 v[42:45], v[162:165], v[206:209], v[42:45]
	v_mfma_f32_16x16x32_bf16 v[26:29], v[162:165], v[214:217], v[26:29]
	v_mfma_f32_16x16x32_bf16 v[18:21], v[178:181], v[214:217], v[18:21]
	v_mfma_f32_16x16x32_bf16 v[2:5], v[178:181], v[234:237], v[2:5]
	v_mfma_f32_16x16x32_bf16 v[10:13], v[162:165], v[234:237], v[10:13]
	s_setprio 0
	s_barrier
; #define PG8_STAGE(bufoff, gbase, voff) do { _Pragma("unroll") for (int _i = 0; _i < 2; ++_i) \
;         __builtin_amdgcn_global_load_lds((const unsigned*)((const char*)(gbase) + (voff)[_i]), (PG8_LAS unsigned*)(lds + (bufoff) + ldsw + _i * 8192), 16, 0, 0); } while (0)
; #define PG8_LDA(dst, b, h) do { _Pragma("unroll") for (int m = 0; m < 4; ++m) _Pragma("unroll") for (int k = 0; k < 2; ++k) dst[m][k] = *(const PG8_LAS bf16x8*)(lds + PG8_SA(b, h) + aoff + m * 2048 + k * 1024); } while (0)
; #define PG8_LDB(dst, b, h) do { _Pragma("unroll") for (int n = 0; n < 2; ++n) _Pragma("unroll") for (int k = 0; k < 2; ++k) dst[n][k] = *(const PG8_LAS bf16x8*)(lds + PG8_SB(b, h) + boff + n * 2048 + k * 1024); } while (0)
; #define PG8_MMA(ai, bj, At, Bt) do { __builtin_amdgcn_s_setprio(1); _Pragma("unroll") for (int m = 0; m < 4; ++m) _Pragma("unroll") for (int n = 0; n < 2; ++n) _Pragma("unroll") for (int k = 0; k < 2; ++k) \
;         acc[ai][bj][m][n] = __builtin_amdgcn_mfma_f32_16x16x32_bf16(Bt[n][k], At[m][k], acc[ai][bj][m][n], 0, 0, 0); __builtin_amdgcn_s_setprio(0); } while (0)
; #define PG8_WAIT_V(n) asm volatile("s_waitcnt vmcnt(" #n ")" ::: "memory")
; #define PG8_WAIT_L(n) asm volatile("s_waitcnt lgkmcnt(" #n ")" ::: "memory")
; #define PG8_BAR __builtin_amdgcn_s_barrier()
; #define PG8_SCHED __builtin_amdgcn_sched_barrier(0)
; template <class Epi, class Sched, bool ALIGN_EPI = false, bool SP2 = false>
; __device__ __forceinline__ void gemm_phase(PG8_LAS unsigned char* lds, const Gemm g, const Sched& S, const Epi& E, const int wave_id) {
;     ...
;             PG8_LDB(B0, 1, 0); PG8_LDB(B1, 1, 1); PG8_SCHED; PG8_LDA(At, 1, 0); PG8_STAGE(PG8_SA(0, 1), a2 + hstep, voffA);
;             PG8_WAIT_V(8); PG8_WAIT_L(0); PG8_BAR; PG8_MMA(0, 0, At, B0); PG8_MMA(0, 1, At, B1); PG8_BAR; PG8_SCHED;
;             PG8_LDA(At, 1, 1); PG8_STAGE(PG8_SB(1, 0), b3, voffB); PG8_STAGE(PG8_SB(1, 1), b3 + hstep, voffB); PG8_STAGE(PG8_SA(1, 0), a3, voffA);
;             PG8_WAIT_V(8); PG8_WAIT_L(0); PG8_BAR; PG8_MMA(1, 0, At, B0); PG8_MMA(1, 1, At, B1); PG8_BAR; PG8_SCHED;
	s_add_i32 s76, 0, 0x18000
	s_add_i32 s77, 0, 0x1c000
	s_add_u32 s44, s44, 0x80000
	s_addc_u32 s45, s45, 0
	s_mov_b32 m0, s64
	s_nop 0
	global_load_lds_dwordx4 v130, s[44:45]
	ds_read_b128 v[142:145], v230 offset:32768
	ds_read_b128 v[146:149], v230 offset:33792
	ds_read_b128 v[150:153], v230 offset:34816
	ds_read_b128 v[154:157], v230 offset:35840
	ds_read_b128 v[158:161], v230 offset:49152
	ds_read_b128 v[162:165], v230 offset:50176
	ds_read_b128 v[166:169], v230 offset:51200
	ds_read_b128 v[178:181], v230 offset:52224
	s_mov_b32 m0, s65
	s_nop 0
	global_load_lds_dwordx4 v134, s[44:45]
	ds_read_b128 v[182:185], v175 offset:32768
	ds_read_b128 v[186:189], v175 offset:33792
	ds_read_b128 v[190:193], v175 offset:34816
	ds_read_b128 v[206:209], v175 offset:35840
	ds_read_b128 v[210:213], v175 offset:36864
	ds_read_b128 v[214:217], v175 offset:37888
	ds_read_b128 v[226:229], v175 offset:38912
	ds_read_b128 v[234:237], v175 offset:39936
	s_waitcnt vmcnt(8)
	s_waitcnt lgkmcnt(0)
	s_barrier
	s_setprio 1
	s_waitcnt lgkmcnt(0)
	v_mfma_f32_16x16x32_bf16 v[126:129], v[142:145], v[182:185], v[126:129]
	v_mfma_f32_16x16x32_bf16 v[118:121], v[150:153], v[182:185], v[118:121]
	v_mfma_f32_16x16x32_bf16 v[102:105], v[150:153], v[190:193], v[102:105]
	v_mfma_f32_16x16x32_bf16 v[110:113], v[142:145], v[190:193], v[110:113]
	v_mfma_f32_16x16x32_bf16 v[94:97], v[142:145], v[210:213], v[94:97]
	v_mfma_f32_16x16x32_bf16 v[86:89], v[150:153], v[210:213], v[86:89]
	v_mfma_f32_16x16x32_bf16 v[70:73], v[150:153], v[226:229], v[70:73]
	v_mfma_f32_16x16x32_bf16 v[78:81], v[142:145], v[226:229], v[78:81]
	v_mfma_f32_16x16x32_bf16 v[126:129], v[146:149], v[186:189], v[126:129]
	v_mfma_f32_16x16x32_bf16 v[118:121], v[154:157], v[186:189], v[118:121]
	v_mfma_f32_16x16x32_bf16 v[102:105], v[154:157], v[206:209], v[102:105]
	v_mfma_f32_16x16x32_bf16 v[110:113], v[146:149], v[206:209], v[110:113]
	v_mfma_f32_16x16x32_bf16 v[94:97], v[146:149], v[214:217], v[94:97]
	v_mfma_f32_16x16x32_bf16 v[86:89], v[154:157], v[214:217], v[86:89]
	v_mfma_f32_16x16x32_bf16 v[70:73], v[154:157], v[234:237], v[70:73]
	v_mfma_f32_16x16x32_bf16 v[78:81], v[146:149], v[234:237], v[78:81]
	s_setprio 0
	s_setprio 1
	v_mfma_f32_16x16x32_bf16 v[122:125], v[158:161], v[182:185], v[122:125]
	v_mfma_f32_16x16x32_bf16 v[114:117], v[166:169], v[182:185], v[114:117]
	v_mfma_f32_16x16x32_bf16 v[98:101], v[166:169], v[190:193], v[98:101]
	v_mfma_f32_16x16x32_bf16 v[106:109], v[158:161], v[190:193], v[106:109]
	v_mfma_f32_16x16x32_bf16 v[90:93], v[158:161], v[210:213], v[90:93]
	v_mfma_f32_16x16x32_bf16 v[82:85], v[166:169], v[210:213], v[82:85]
	v_mfma_f32_16x16x32_bf16 v[66:69], v[166:169], v[226:229], v[66:69]
	v_mfma_f32_16x16x32_bf16 v[74:77], v[158:161], v[226:229], v[74:77]
	v_mfma_f32_16x16x32_bf16 v[122:125], v[162:165], v[186:189], v[122:125]
	v_mfma_f32_16x16x32_bf16 v[114:117], v[178:181], v[186:189], v[114:117]
	v_mfma_f32_16x16x32_bf16 v[98:101], v[178:181], v[206:209], v[98:101]
	v_mfma_f32_16x16x32_bf16 v[106:109], v[162:165], v[206:209], v[106:109]
	v_mfma_f32_16x16x32_bf16 v[90:93], v[162:165], v[214:217], v[90:93]
	v_mfma_f32_16x16x32_bf16 v[82:85], v[178:181], v[214:217], v[82:85]
	v_mfma_f32_16x16x32_bf16 v[66:69], v[178:181], v[234:237], v[66:69]
	v_mfma_f32_16x16x32_bf16 v[74:77], v[162:165], v[234:237], v[74:77]
	s_setprio 0
	s_barrier
	s_add_u32 vcc_lo, s44, 0xfff80080
	s_addc_u32 vcc_hi, s45, -1
	s_mov_b32 m0, s68
	s_nop 0
	global_load_lds_dwordx4 v130, vcc
	ds_read_b128 v[182:185], v175 offset:49152
	ds_read_b128 v[186:189], v175 offset:50176
	s_mov_b32 m0, s69
	s_add_i32 s44, s76, s53
	global_load_lds_dwordx4 v134, vcc
	ds_read_b128 v[190:193], v175 offset:51200
	ds_read_b128 v[206:209], v175 offset:52224
	s_add_u32 vcc_lo, s42, 0x80
	s_addc_u32 vcc_hi, s43, 0
	s_mov_b32 m0, s44
	s_nop 0
	global_load_lds_dwordx4 v132, vcc
	ds_read_b128 v[210:213], v175 offset:53248
	ds_read_b128 v[214:217], v175 offset:54272
	s_add_i32 m0, s44, 0x2000
	s_add_u32 s42, s42, 0x80080
	s_addc_u32 s43, s43, 0
	global_load_lds_dwordx4 v136, vcc
	ds_read_b128 v[226:229], v175 offset:55296
	ds_read_b128 v[234:237], v175 offset:56320
	s_add_i32 s44, s77, s53
	s_mov_b32 m0, s44
	s_nop 0
	global_load_lds_dwordx4 v132, s[42:43]
	s_add_i32 m0, s44, 0x2000
	s_nop 0
	global_load_lds_dwordx4 v136, s[42:43]
	s_waitcnt vmcnt(8)
	s_waitcnt lgkmcnt(0)
	s_barrier
	s_setprio 1
	s_waitcnt lgkmcnt(0)
	v_mfma_f32_16x16x32_bf16 v[62:65], v[142:145], v[182:185], v[62:65]
	v_mfma_f32_16x16x32_bf16 v[54:57], v[150:153], v[182:185], v[54:57]
	v_mfma_f32_16x16x32_bf16 v[38:41], v[150:153], v[190:193], v[38:41]
	v_mfma_f32_16x16x32_bf16 v[46:49], v[142:145], v[190:193], v[46:49]
	v_mfma_f32_16x16x32_bf16 v[30:33], v[142:145], v[210:213], v[30:33]
	v_mfma_f32_16x16x32_bf16 v[22:25], v[150:153], v[210:213], v[22:25]
	v_mfma_f32_16x16x32_bf16 v[6:9], v[150:153], v[226:229], v[6:9]
	v_mfma_f32_16x16x32_bf16 v[14:17], v[142:145], v[226:229], v[14:17]
	v_mfma_f32_16x16x32_bf16 v[62:65], v[146:149], v[186:189], v[62:65]
	v_mfma_f32_16x16x32_bf16 v[54:57], v[154:157], v[186:189], v[54:57]
	v_mfma_f32_16x16x32_bf16 v[38:41], v[154:157], v[206:209], v[38:41]
	v_mfma_f32_16x16x32_bf16 v[46:49], v[146:149], v[206:209], v[46:49]
	v_mfma_f32_16x16x32_bf16 v[30:33], v[146:149], v[214:217], v[30:33]
	v_mfma_f32_16x16x32_bf16 v[22:25], v[154:157], v[214:217], v[22:25]
	v_mfma_f32_16x16x32_bf16 v[6:9], v[154:157], v[234:237], v[6:9]
	v_mfma_f32_16x16x32_bf16 v[14:17], v[146:149], v[234:237], v[14:17]
	s_setprio 0
	s_setprio 1
	v_mfma_f32_16x16x32_bf16 v[58:61], v[158:161], v[182:185], v[58:61]
	v_mfma_f32_16x16x32_bf16 v[50:53], v[166:169], v[182:185], v[50:53]
	v_mfma_f32_16x16x32_bf16 v[34:37], v[166:169], v[190:193], v[34:37]
	v_mfma_f32_16x16x32_bf16 v[42:45], v[158:161], v[190:193], v[42:45]
	v_mfma_f32_16x16x32_bf16 v[26:29], v[158:161], v[210:213], v[26:29]
	v_mfma_f32_16x16x32_bf16 v[18:21], v[166:169], v[210:213], v[18:21]
	v_mfma_f32_16x16x32_bf16 v[2:5], v[166:169], v[226:229], v[2:5]
	v_mfma_f32_16x16x32_bf16 v[10:13], v[158:161], v[226:229], v[10:13]
	v_mfma_f32_16x16x32_bf16 v[58:61], v[162:165], v[186:189], v[58:61]
	v_mfma_f32_16x16x32_bf16 v[50:53], v[178:181], v[186:189], v[50:53]
	v_mfma_f32_16x16x32_bf16 v[34:37], v[178:181], v[206:209], v[34:37]
	v_mfma_f32_16x16x32_bf16 v[42:45], v[162:165], v[206:209], v[42:45]
	v_mfma_f32_16x16x32_bf16 v[26:29], v[162:165], v[214:217], v[26:29]
	v_mfma_f32_16x16x32_bf16 v[18:21], v[178:181], v[214:217], v[18:21]
	v_mfma_f32_16x16x32_bf16 v[2:5], v[178:181], v[234:237], v[2:5]
	v_mfma_f32_16x16x32_bf16 v[10:13], v[162:165], v[234:237], v[10:13]
	s_setprio 0
	s_barrier
	s_add_i32 s75, s75, 2
	s_add_u32 s20, s20, 0x100
	s_addc_u32 s21, s21, 0
	s_add_u32 s73, s73, 0x100
	s_addc_u32 s74, s74, 0
	s_cmp_gt_u32 s75, 29
	s_cbranch_scc0 .LBB0_174
	s_and_b64 vcc, exec, s[10:11]
	s_cbranch_vccz .LBB0_177
	s_barrier

; #define PG8_STAGE(bufoff, gbase, voff) do { _Pragma("unroll") for (int _i = 0; _i < 2; ++_i) \
;         __builtin_amdgcn_global_load_lds((const unsigned*)((const char*)(gbase) + (voff)[_i]), (PG8_LAS unsigned*)(lds + (bufoff) + ldsw + _i * 8192), 16, 0, 0); } while (0)
; #define PG8_LDA(dst, b, h) do { _Pragma("unroll") for (int m = 0; m < 4; ++m) _Pragma("unroll") for (int k = 0; k < 2; ++k) dst[m][k] = *(const PG8_LAS bf16x8*)(lds + PG8_SA(b, h) + aoff + m * 2048 + k * 1024); } while (0)
; #define PG8_LDB(dst, b, h) do { _Pragma("unroll") for (int n = 0; n < 2; ++n) _Pragma("unroll") for (int k = 0; k < 2; ++k) dst[n][k] = *(const PG8_LAS bf16x8*)(lds + PG8_SB(b, h) + boff + n * 2048 + k * 1024); } while (0)
; #define PG8_MMA(ai, bj, At, Bt) do { __builtin_amdgcn_s_setprio(1); _Pragma("unroll") for (int m = 0; m < 4; ++m) _Pragma("unroll") for (int n = 0; n < 2; ++n) _Pragma("unroll") for (int k = 0; k < 2; ++k) \
;         acc[ai][bj][m][n] = __builtin_amdgcn_mfma_f32_16x16x32_bf16(Bt[n][k], At[m][k], acc[ai][bj][m][n], 0, 0, 0); __builtin_amdgcn_s_setprio(0); } while (0)
; #define PG8_WAIT_V(n) asm volatile("s_waitcnt vmcnt(" #n ")" ::: "memory")
; #define PG8_WAIT_L(n) asm volatile("s_waitcnt lgkmcnt(" #n ")" ::: "memory")
; template <class Epi, class Sched, bool ALIGN_EPI = false, bool SP2 = false>
; __device__ __forceinline__ void gemm_phase(PG8_LAS unsigned char* lds, const Gemm g, const Sched& S, const Epi& E, const int wave_id) {
;     ...
;             const bool last = (t == nt - 2);
;             const char* a1 = cA + (size_t)(t + 1) * kstep;
;             const char* a2 = last ? nA : cA + (size_t)(t + 2) * kstep; const char* b2 = last ? nB : cB + (size_t)(t + 2) * kstep;
;             const char* a3 = a2 + kstep; const char* b3 = b2 + kstep;
;             if (last && has_next) S.a_ready(nxt);
;             if constexpr (SP2) {
;             PG8_LDB(B0, 0, 0); PG8_LDB(B1, 0, 1); PG8_SCHED; PG8_LDA(At, 0, 0); PG8_STAGE(PG8_SA(1, 1), a1 + hstep, voffA);
;             PG8_WAIT_V(8); PG8_WAIT_L(0); PG8_BAR; PG8_MMA(0, 0, At, B0); PG8_MMA(0, 1, At, B1); PG8_BAR; PG8_SCHED;
;             PG8_LDA(At, 0, 1); PG8_STAGE(PG8_SB(0, 0), b2, voffB); PG8_STAGE(PG8_SB(0, 1), b2 + hstep, voffB); PG8_STAGE(PG8_SA(0, 0), a2, voffA);
;             PG8_WAIT_V(8); PG8_WAIT_L(0); PG8_BAR; PG8_MMA(1, 0, At, B0); PG8_MMA(1, 1, At, B1); PG8_BAR; PG8_SCHED;
.LBB0_524:
	s_add_u32 s42, s40, 0xfff80080
	s_addc_u32 s43, s41, -1
	s_add_i32 s77, 0, 0x10000
	s_cmp_eq_u32 s76, 28
	s_cselect_b32 s45, s15, s43
	s_cselect_b32 s44, s21, s42
	s_cselect_b32 s43, s13, s75
	s_cselect_b32 s42, s73, s74
	s_add_i32 s79, 0, 0x14000
	s_add_i32 m0, s56, 0xc000
	s_nop 0
	global_load_lds_dwordx4 v210, s[40:41]
	ds_read_b128 v[118:121], v226
	ds_read_b128 v[122:125], v226 offset:1024
	ds_read_b128 v[130:133], v226 offset:2048
	ds_read_b128 v[134:137], v226 offset:3072
	ds_read_b128 v[146:149], v226 offset:16384
	ds_read_b128 v[150:153], v226 offset:17408
	ds_read_b128 v[154:157], v226 offset:18432
	ds_read_b128 v[158:161], v226 offset:19456
	s_add_i32 m0, s56, 0xe000
	s_nop 0
	global_load_lds_dwordx4 v212, s[40:41]
	ds_read_b128 v[162:165], v222
	ds_read_b128 v[166:169], v222 offset:1024
	ds_read_b128 v[170:173], v222 offset:2048
	ds_read_b128 v[174:177], v222 offset:3072
	ds_read_b128 v[178:181], v222 offset:4096
	ds_read_b128 v[182:185], v222 offset:5120
	ds_read_b128 v[186:189], v222 offset:6144
	ds_read_b128 v[214:217], v222 offset:7168
	s_waitcnt vmcnt(8)
	s_waitcnt lgkmcnt(0)
	s_barrier
	s_setprio 1
	s_waitcnt lgkmcnt(0)
	v_mfma_f32_16x16x32_bf16 v[142:145], v[118:121], v[162:165], v[142:145]
	v_mfma_f32_16x16x32_bf16 v[138:141], v[130:133], v[162:165], v[138:141]
	v_mfma_f32_16x16x32_bf16 v[106:109], v[130:133], v[170:173], v[106:109]
	v_mfma_f32_16x16x32_bf16 v[110:113], v[118:121], v[170:173], v[110:113]
	v_mfma_f32_16x16x32_bf16 v[94:97], v[118:121], v[178:181], v[94:97]
	v_mfma_f32_16x16x32_bf16 v[90:93], v[130:133], v[178:181], v[90:93]
	v_mfma_f32_16x16x32_bf16 v[74:77], v[130:133], v[186:189], v[74:77]
	v_mfma_f32_16x16x32_bf16 v[78:81], v[118:121], v[186:189], v[78:81]
	v_mfma_f32_16x16x32_bf16 v[142:145], v[122:125], v[166:169], v[142:145]
	v_mfma_f32_16x16x32_bf16 v[138:141], v[134:137], v[166:169], v[138:141]
	v_mfma_f32_16x16x32_bf16 v[106:109], v[134:137], v[174:177], v[106:109]
	v_mfma_f32_16x16x32_bf16 v[110:113], v[122:125], v[174:177], v[110:113]
	v_mfma_f32_16x16x32_bf16 v[94:97], v[122:125], v[182:185], v[94:97]
	v_mfma_f32_16x16x32_bf16 v[90:93], v[134:137], v[182:185], v[90:93]
	v_mfma_f32_16x16x32_bf16 v[74:77], v[134:137], v[214:217], v[74:77]
	v_mfma_f32_16x16x32_bf16 v[78:81], v[122:125], v[214:217], v[78:81]
	s_setprio 0
	s_setprio 1
	v_mfma_f32_16x16x32_bf16 v[126:129], v[146:149], v[162:165], v[126:129]
	v_mfma_f32_16x16x32_bf16 v[114:117], v[154:157], v[162:165], v[114:117]
	v_mfma_f32_16x16x32_bf16 v[98:101], v[154:157], v[170:173], v[98:101]
	v_mfma_f32_16x16x32_bf16 v[102:105], v[146:149], v[170:173], v[102:105]
	v_mfma_f32_16x16x32_bf16 v[86:89], v[146:149], v[178:181], v[86:89]
	v_mfma_f32_16x16x32_bf16 v[82:85], v[154:157], v[178:181], v[82:85]
	v_mfma_f32_16x16x32_bf16 v[66:69], v[154:157], v[186:189], v[66:69]
	v_mfma_f32_16x16x32_bf16 v[70:73], v[146:149], v[186:189], v[70:73]
	v_mfma_f32_16x16x32_bf16 v[126:129], v[150:153], v[166:169], v[126:129]
	v_mfma_f32_16x16x32_bf16 v[114:117], v[158:161], v[166:169], v[114:117]
	v_mfma_f32_16x16x32_bf16 v[98:101], v[158:161], v[174:177], v[98:101]
	v_mfma_f32_16x16x32_bf16 v[102:105], v[150:153], v[174:177], v[102:105]
	v_mfma_f32_16x16x32_bf16 v[86:89], v[150:153], v[182:185], v[86:89]
	v_mfma_f32_16x16x32_bf16 v[82:85], v[158:161], v[182:185], v[82:85]
	v_mfma_f32_16x16x32_bf16 v[66:69], v[158:161], v[214:217], v[66:69]
	v_mfma_f32_16x16x32_bf16 v[70:73], v[150:153], v[214:217], v[70:73]
	s_setprio 0
	s_barrier
	s_add_i32 s77, s77, s53
	s_mov_b32 m0, s77
	s_nop 0
	global_load_lds_dwordx4 v192, s[42:43]
	ds_read_b128 v[162:165], v222 offset:16384
	ds_read_b128 v[166:169], v222 offset:17408
	s_add_i32 m0, s77, 0x2000
	s_add_u32 s80, s42, 0x80000
	s_addc_u32 s81, s43, 0
	s_add_i32 s77, s79, s53
	global_load_lds_dwordx4 v208, s[42:43]
	ds_read_b128 v[170:173], v222 offset:18432
	ds_read_b128 v[174:177], v222 offset:19456
	s_mov_b32 m0, s77
	s_nop 0
	global_load_lds_dwordx4 v192, s[80:81]
	ds_read_b128 v[178:181], v222 offset:20480
	ds_read_b128 v[182:185], v222 offset:21504
	s_add_i32 m0, s77, 0x2000
	s_nop 0
	global_load_lds_dwordx4 v208, s[80:81]
	ds_read_b128 v[186:189], v222 offset:22528
	ds_read_b128 v[214:217], v222 offset:23552
	s_mov_b32 m0, s56
	s_nop 0
	global_load_lds_dwordx4 v190, s[44:45]
	s_mov_b32 m0, s57
	s_nop 0
	global_load_lds_dwordx4 v206, s[44:45]
	s_waitcnt vmcnt(8)
	s_waitcnt lgkmcnt(0)
	s_barrier
	s_setprio 1
	s_waitcnt lgkmcnt(0)
	v_mfma_f32_16x16x32_bf16 v[62:65], v[118:121], v[162:165], v[62:65]
	v_mfma_f32_16x16x32_bf16 v[58:61], v[130:133], v[162:165], v[58:61]
	v_mfma_f32_16x16x32_bf16 v[42:45], v[130:133], v[170:173], v[42:45]
	v_mfma_f32_16x16x32_bf16 v[46:49], v[118:121], v[170:173], v[46:49]
	v_mfma_f32_16x16x32_bf16 v[30:33], v[118:121], v[178:181], v[30:33]
	v_mfma_f32_16x16x32_bf16 v[26:29], v[130:133], v[178:181], v[26:29]
	v_mfma_f32_16x16x32_bf16 v[10:13], v[130:133], v[186:189], v[10:13]
	v_mfma_f32_16x16x32_bf16 v[14:17], v[118:121], v[186:189], v[14:17]
	v_mfma_f32_16x16x32_bf16 v[62:65], v[122:125], v[166:169], v[62:65]
	v_mfma_f32_16x16x32_bf16 v[58:61], v[134:137], v[166:169], v[58:61]
	v_mfma_f32_16x16x32_bf16 v[42:45], v[134:137], v[174:177], v[42:45]
	v_mfma_f32_16x16x32_bf16 v[46:49], v[122:125], v[174:177], v[46:49]
	v_mfma_f32_16x16x32_bf16 v[30:33], v[122:125], v[182:185], v[30:33]
	v_mfma_f32_16x16x32_bf16 v[26:29], v[134:137], v[182:185], v[26:29]
	v_mfma_f32_16x16x32_bf16 v[10:13], v[134:137], v[214:217], v[10:13]
	v_mfma_f32_16x16x32_bf16 v[14:17], v[122:125], v[214:217], v[14:17]
	s_setprio 0
	s_setprio 1
	v_mfma_f32_16x16x32_bf16 v[54:57], v[146:149], v[162:165], v[54:57]
	v_mfma_f32_16x16x32_bf16 v[50:53], v[154:157], v[162:165], v[50:53]
	v_mfma_f32_16x16x32_bf16 v[34:37], v[154:157], v[170:173], v[34:37]
	v_mfma_f32_16x16x32_bf16 v[38:41], v[146:149], v[170:173], v[38:41]
	v_mfma_f32_16x16x32_bf16 v[22:25], v[146:149], v[178:181], v[22:25]
	v_mfma_f32_16x16x32_bf16 v[18:21], v[154:157], v[178:181], v[18:21]
	v_mfma_f32_16x16x32_bf16 v[2:5], v[154:157], v[186:189], v[2:5]
	v_mfma_f32_16x16x32_bf16 v[6:9], v[146:149], v[186:189], v[6:9]
	v_mfma_f32_16x16x32_bf16 v[54:57], v[150:153], v[166:169], v[54:57]
	v_mfma_f32_16x16x32_bf16 v[50:53], v[158:161], v[166:169], v[50:53]
	v_mfma_f32_16x16x32_bf16 v[34:37], v[158:161], v[174:177], v[34:37]
	v_mfma_f32_16x16x32_bf16 v[38:41], v[150:153], v[174:177], v[38:41]
	v_mfma_f32_16x16x32_bf16 v[22:25], v[150:153], v[182:185], v[22:25]
	v_mfma_f32_16x16x32_bf16 v[18:21], v[158:161], v[182:185], v[18:21]
	v_mfma_f32_16x16x32_bf16 v[2:5], v[158:161], v[214:217], v[2:5]
	v_mfma_f32_16x16x32_bf16 v[6:9], v[150:153], v[214:217], v[6:9]
	s_setprio 0
	s_barrier
; #define PG8_STAGE(bufoff, gbase, voff) do { _Pragma("unroll") for (int _i = 0; _i < 2; ++_i) \
;         __builtin_amdgcn_global_load_lds((const unsigned*)((const char*)(gbase) + (voff)[_i]), (PG8_LAS unsigned*)(lds + (bufoff) + ldsw + _i * 8192), 16, 0, 0); } while (0)
; #define PG8_LDA(dst, b, h) do { _Pragma("unroll") for (int m = 0; m < 4; ++m) _Pragma("unroll") for (int k = 0; k < 2; ++k) dst[m][k] = *(const PG8_LAS bf16x8*)(lds + PG8_SA(b, h) + aoff + m * 2048 + k * 1024); } while (0)
; #define PG8_LDB(dst, b, h) do { _Pragma("unroll") for (int n = 0; n < 2; ++n) _Pragma("unroll") for (int k = 0; k < 2; ++k) dst[n][k] = *(const PG8_LAS bf16x8*)(lds + PG8_SB(b, h) + boff + n * 2048 + k * 1024); } while (0)
; #define PG8_MMA(ai, bj, At, Bt) do { __builtin_amdgcn_s_setprio(1); _Pragma("unroll") for (int m = 0; m < 4; ++m) _Pragma("unroll") for (int n = 0; n < 2; ++n) _Pragma("unroll") for (int k = 0; k < 2; ++k) \
;         acc[ai][bj][m][n] = __builtin_amdgcn_mfma_f32_16x16x32_bf16(Bt[n][k], At[m][k], acc[ai][bj][m][n], 0, 0, 0); __builtin_amdgcn_s_setprio(0); } while (0)
; #define PG8_WAIT_V(n) asm volatile("s_waitcnt vmcnt(" #n ")" ::: "memory")
; #define PG8_WAIT_L(n) asm volatile("s_waitcnt lgkmcnt(" #n ")" ::: "memory")
; #define PG8_BAR __builtin_amdgcn_s_barrier()
; #define PG8_SCHED __builtin_amdgcn_sched_barrier(0)
; template <class Epi, class Sched, bool ALIGN_EPI = false, bool SP2 = false>
; __device__ __forceinline__ void gemm_phase(PG8_LAS unsigned char* lds, const Gemm g, const Sched& S, const Epi& E, const int wave_id) {
;     ...
;             PG8_LDB(B0, 1, 0); PG8_LDB(B1, 1, 1); PG8_SCHED; PG8_LDA(At, 1, 0); PG8_STAGE(PG8_SA(0, 1), a2 + hstep, voffA);
;             PG8_WAIT_V(8); PG8_WAIT_L(0); PG8_BAR; PG8_MMA(0, 0, At, B0); PG8_MMA(0, 1, At, B1); PG8_BAR; PG8_SCHED;
;             PG8_LDA(At, 1, 1); PG8_STAGE(PG8_SB(1, 0), b3, voffB); PG8_STAGE(PG8_SB(1, 1), b3 + hstep, voffB); PG8_STAGE(PG8_SA(1, 0), a3, voffA);
;             PG8_WAIT_V(8); PG8_WAIT_L(0); PG8_BAR; PG8_MMA(1, 0, At, B0); PG8_MMA(1, 1, At, B1); PG8_BAR; PG8_SCHED;
;     ...
;         if constexpr (ALIGN_EPI) { if (wr == 0) PG8_BAR; }
	s_add_i32 s77, 0, 0x18000
	s_add_i32 s79, 0, 0x1c000
	s_add_u32 s44, s44, 0x80000
	s_addc_u32 s45, s45, 0
	s_mov_b32 m0, s64
	s_nop 0
	global_load_lds_dwordx4 v190, s[44:45]
	ds_read_b128 v[118:121], v226 offset:32768
	ds_read_b128 v[122:125], v226 offset:33792
	ds_read_b128 v[130:133], v226 offset:34816
	ds_read_b128 v[134:137], v226 offset:35840
	ds_read_b128 v[146:149], v226 offset:49152
	ds_read_b128 v[150:153], v226 offset:50176
	ds_read_b128 v[154:157], v226 offset:51200
	ds_read_b128 v[158:161], v226 offset:52224
	s_mov_b32 m0, s65
	s_nop 0
	global_load_lds_dwordx4 v206, s[44:45]
	ds_read_b128 v[162:165], v222 offset:32768
	ds_read_b128 v[166:169], v222 offset:33792
	ds_read_b128 v[170:173], v222 offset:34816
	ds_read_b128 v[174:177], v222 offset:35840
	ds_read_b128 v[178:181], v222 offset:36864
	ds_read_b128 v[182:185], v222 offset:37888
	ds_read_b128 v[186:189], v222 offset:38912
	ds_read_b128 v[214:217], v222 offset:39936
	s_waitcnt vmcnt(8)
	s_waitcnt lgkmcnt(0)
	s_barrier
	s_setprio 1
	s_waitcnt lgkmcnt(0)
	v_mfma_f32_16x16x32_bf16 v[142:145], v[118:121], v[162:165], v[142:145]
	v_mfma_f32_16x16x32_bf16 v[138:141], v[130:133], v[162:165], v[138:141]
	v_mfma_f32_16x16x32_bf16 v[106:109], v[130:133], v[170:173], v[106:109]
	v_mfma_f32_16x16x32_bf16 v[110:113], v[118:121], v[170:173], v[110:113]
	v_mfma_f32_16x16x32_bf16 v[94:97], v[118:121], v[178:181], v[94:97]
	v_mfma_f32_16x16x32_bf16 v[90:93], v[130:133], v[178:181], v[90:93]
	v_mfma_f32_16x16x32_bf16 v[74:77], v[130:133], v[186:189], v[74:77]
	v_mfma_f32_16x16x32_bf16 v[78:81], v[118:121], v[186:189], v[78:81]
	v_mfma_f32_16x16x32_bf16 v[142:145], v[122:125], v[166:169], v[142:145]
	v_mfma_f32_16x16x32_bf16 v[138:141], v[134:137], v[166:169], v[138:141]
	v_mfma_f32_16x16x32_bf16 v[106:109], v[134:137], v[174:177], v[106:109]
	v_mfma_f32_16x16x32_bf16 v[110:113], v[122:125], v[174:177], v[110:113]
	v_mfma_f32_16x16x32_bf16 v[94:97], v[122:125], v[182:185], v[94:97]
	v_mfma_f32_16x16x32_bf16 v[90:93], v[134:137], v[182:185], v[90:93]
	v_mfma_f32_16x16x32_bf16 v[74:77], v[134:137], v[214:217], v[74:77]
	v_mfma_f32_16x16x32_bf16 v[78:81], v[122:125], v[214:217], v[78:81]
	s_setprio 0
	s_setprio 1
	v_mfma_f32_16x16x32_bf16 v[126:129], v[146:149], v[162:165], v[126:129]
	v_mfma_f32_16x16x32_bf16 v[114:117], v[154:157], v[162:165], v[114:117]
	v_mfma_f32_16x16x32_bf16 v[98:101], v[154:157], v[170:173], v[98:101]
	v_mfma_f32_16x16x32_bf16 v[102:105], v[146:149], v[170:173], v[102:105]
	v_mfma_f32_16x16x32_bf16 v[86:89], v[146:149], v[178:181], v[86:89]
	v_mfma_f32_16x16x32_bf16 v[82:85], v[154:157], v[178:181], v[82:85]
	v_mfma_f32_16x16x32_bf16 v[66:69], v[154:157], v[186:189], v[66:69]
	v_mfma_f32_16x16x32_bf16 v[70:73], v[146:149], v[186:189], v[70:73]
	v_mfma_f32_16x16x32_bf16 v[126:129], v[150:153], v[166:169], v[126:129]
	v_mfma_f32_16x16x32_bf16 v[114:117], v[158:161], v[166:169], v[114:117]
	v_mfma_f32_16x16x32_bf16 v[98:101], v[158:161], v[174:177], v[98:101]
	v_mfma_f32_16x16x32_bf16 v[102:105], v[150:153], v[174:177], v[102:105]
	v_mfma_f32_16x16x32_bf16 v[86:89], v[150:153], v[182:185], v[86:89]
	v_mfma_f32_16x16x32_bf16 v[82:85], v[158:161], v[182:185], v[82:85]
	v_mfma_f32_16x16x32_bf16 v[66:69], v[158:161], v[214:217], v[66:69]
	v_mfma_f32_16x16x32_bf16 v[70:73], v[150:153], v[214:217], v[70:73]
	s_setprio 0
	s_barrier
	s_add_u32 vcc_lo, s44, 0xfff80080
	s_addc_u32 vcc_hi, s45, -1
	s_mov_b32 m0, s70
	s_nop 0
	global_load_lds_dwordx4 v190, vcc
	ds_read_b128 v[162:165], v222 offset:49152
	ds_read_b128 v[166:169], v222 offset:50176
	s_mov_b32 m0, s71
	s_add_i32 s44, s77, s53
	global_load_lds_dwordx4 v206, vcc
	ds_read_b128 v[170:173], v222 offset:51200
	ds_read_b128 v[174:177], v222 offset:52224
	s_add_u32 vcc_lo, s42, 0x80
	s_addc_u32 vcc_hi, s43, 0
	s_mov_b32 m0, s44
	s_nop 0
	global_load_lds_dwordx4 v192, vcc
	ds_read_b128 v[178:181], v222 offset:53248
	ds_read_b128 v[182:185], v222 offset:54272
	s_add_i32 m0, s44, 0x2000
	s_add_u32 s42, s42, 0x80080
	s_addc_u32 s43, s43, 0
	global_load_lds_dwordx4 v208, vcc
	ds_read_b128 v[186:189], v222 offset:55296
	ds_read_b128 v[214:217], v222 offset:56320
	s_add_i32 s44, s79, s53
	s_mov_b32 m0, s44
	s_nop 0
	global_load_lds_dwordx4 v192, s[42:43]
	s_add_i32 m0, s44, 0x2000
	s_nop 0
	global_load_lds_dwordx4 v208, s[42:43]
	s_waitcnt vmcnt(8)
	s_waitcnt lgkmcnt(0)
	s_barrier
	s_setprio 1
	s_waitcnt lgkmcnt(0)
	v_mfma_f32_16x16x32_bf16 v[62:65], v[118:121], v[162:165], v[62:65]
	v_mfma_f32_16x16x32_bf16 v[58:61], v[130:133], v[162:165], v[58:61]
	v_mfma_f32_16x16x32_bf16 v[42:45], v[130:133], v[170:173], v[42:45]
	v_mfma_f32_16x16x32_bf16 v[46:49], v[118:121], v[170:173], v[46:49]
	v_mfma_f32_16x16x32_bf16 v[30:33], v[118:121], v[178:181], v[30:33]
	v_mfma_f32_16x16x32_bf16 v[26:29], v[130:133], v[178:181], v[26:29]
	v_mfma_f32_16x16x32_bf16 v[10:13], v[130:133], v[186:189], v[10:13]
	v_mfma_f32_16x16x32_bf16 v[14:17], v[118:121], v[186:189], v[14:17]
	v_mfma_f32_16x16x32_bf16 v[62:65], v[122:125], v[166:169], v[62:65]
	v_mfma_f32_16x16x32_bf16 v[58:61], v[134:137], v[166:169], v[58:61]
	v_mfma_f32_16x16x32_bf16 v[42:45], v[134:137], v[174:177], v[42:45]
	v_mfma_f32_16x16x32_bf16 v[46:49], v[122:125], v[174:177], v[46:49]
	v_mfma_f32_16x16x32_bf16 v[30:33], v[122:125], v[182:185], v[30:33]
	v_mfma_f32_16x16x32_bf16 v[26:29], v[134:137], v[182:185], v[26:29]
	v_mfma_f32_16x16x32_bf16 v[10:13], v[134:137], v[214:217], v[10:13]
	v_mfma_f32_16x16x32_bf16 v[14:17], v[122:125], v[214:217], v[14:17]
	s_setprio 0
	s_setprio 1
	v_mfma_f32_16x16x32_bf16 v[54:57], v[146:149], v[162:165], v[54:57]
	v_mfma_f32_16x16x32_bf16 v[50:53], v[154:157], v[162:165], v[50:53]
	v_mfma_f32_16x16x32_bf16 v[34:37], v[154:157], v[170:173], v[34:37]
	v_mfma_f32_16x16x32_bf16 v[38:41], v[146:149], v[170:173], v[38:41]
	v_mfma_f32_16x16x32_bf16 v[22:25], v[146:149], v[178:181], v[22:25]
	v_mfma_f32_16x16x32_bf16 v[18:21], v[154:157], v[178:181], v[18:21]
	v_mfma_f32_16x16x32_bf16 v[2:5], v[154:157], v[186:189], v[2:5]
	v_mfma_f32_16x16x32_bf16 v[6:9], v[146:149], v[186:189], v[6:9]
	v_mfma_f32_16x16x32_bf16 v[54:57], v[150:153], v[166:169], v[54:57]
	v_mfma_f32_16x16x32_bf16 v[50:53], v[158:161], v[166:169], v[50:53]
	v_mfma_f32_16x16x32_bf16 v[34:37], v[158:161], v[174:177], v[34:37]
	v_mfma_f32_16x16x32_bf16 v[38:41], v[150:153], v[174:177], v[38:41]
	v_mfma_f32_16x16x32_bf16 v[22:25], v[150:153], v[182:185], v[22:25]
	v_mfma_f32_16x16x32_bf16 v[18:21], v[158:161], v[182:185], v[18:21]
	v_mfma_f32_16x16x32_bf16 v[2:5], v[158:161], v[214:217], v[2:5]
	v_mfma_f32_16x16x32_bf16 v[6:9], v[150:153], v[214:217], v[6:9]
	s_setprio 0
	s_barrier
	s_add_i32 s76, s76, 2
	s_add_u32 s40, s40, 0x100
	s_addc_u32 s41, s41, 0
	s_add_u32 s74, s74, 0x100
	s_addc_u32 s75, s75, 0
	s_cmp_gt_u32 s76, 29
	s_cbranch_scc0 .LBB0_524
	s_and_b64 vcc, exec, s[10:11]
	s_cbranch_vccz .LBB0_527
	s_barrier

; #define PG8_STAGE(bufoff, gbase, voff) do { _Pragma("unroll") for (int _i = 0; _i < 2; ++_i) \
;         __builtin_amdgcn_global_load_lds((const unsigned*)((const char*)(gbase) + (voff)[_i]), (PG8_LAS unsigned*)(lds + (bufoff) + ldsw + _i * 8192), 16, 0, 0); } while (0)
; #define PG8_LDA(dst, b, h) do { _Pragma("unroll") for (int m = 0; m < 4; ++m) _Pragma("unroll") for (int k = 0; k < 2; ++k) dst[m][k] = *(const PG8_LAS bf16x8*)(lds + PG8_SA(b, h) + aoff + m * 2048 + k * 1024); } while (0)
; #define PG8_LDB(dst, b, h) do { _Pragma("unroll") for (int n = 0; n < 2; ++n) _Pragma("unroll") for (int k = 0; k < 2; ++k) dst[n][k] = *(const PG8_LAS bf16x8*)(lds + PG8_SB(b, h) + boff + n * 2048 + k * 1024); } while (0)
; #define PG8_MMA(ai, bj, At, Bt) do { __builtin_amdgcn_s_setprio(1); _Pragma("unroll") for (int m = 0; m < 4; ++m) _Pragma("unroll") for (int n = 0; n < 2; ++n) _Pragma("unroll") for (int k = 0; k < 2; ++k) \
;         acc[ai][bj][m][n] = __builtin_amdgcn_mfma_f32_16x16x32_bf16(Bt[n][k], At[m][k], acc[ai][bj][m][n], 0, 0, 0); __builtin_amdgcn_s_setprio(0); } while (0)
; #define PG8_WAIT_V(n) asm volatile("s_waitcnt vmcnt(" #n ")" ::: "memory")
; #define PG8_WAIT_L(n) asm volatile("s_waitcnt lgkmcnt(" #n ")" ::: "memory")
; template <class Epi, class Sched, bool ALIGN_EPI = false, bool SP2 = false>
; __device__ __forceinline__ void gemm_phase(PG8_LAS unsigned char* lds, const Gemm g, const Sched& S, const Epi& E, const int wave_id) {
;     ...
;             const bool last = (t == nt - 2);
;             const char* a1 = cA + (size_t)(t + 1) * kstep;
;             const char* a2 = last ? nA : cA + (size_t)(t + 2) * kstep; const char* b2 = last ? nB : cB + (size_t)(t + 2) * kstep;
;             const char* a3 = a2 + kstep; const char* b3 = b2 + kstep;
;             if (last && has_next) S.a_ready(nxt);
;             if constexpr (SP2) {
;             PG8_LDB(B0, 0, 0); PG8_LDB(B1, 0, 1); PG8_SCHED; PG8_LDA(At, 0, 0); PG8_STAGE(PG8_SA(1, 1), a1 + hstep, voffA);
;             PG8_WAIT_V(8); PG8_WAIT_L(0); PG8_BAR; PG8_MMA(0, 0, At, B0); PG8_MMA(0, 1, At, B1); PG8_BAR; PG8_SCHED;
;             PG8_LDA(At, 0, 1); PG8_STAGE(PG8_SB(0, 0), b2, voffB); PG8_STAGE(PG8_SB(0, 1), b2 + hstep, voffB); PG8_STAGE(PG8_SA(0, 0), a2, voffA);
;             PG8_WAIT_V(8); PG8_WAIT_L(0); PG8_BAR; PG8_MMA(1, 0, At, B0); PG8_MMA(1, 1, At, B1); PG8_BAR; PG8_SCHED;
.LBB0_641:
	s_add_u32 s42, s20, 0xfff80080
	s_addc_u32 s43, s21, -1
	s_add_i32 s76, 0, 0x10000
	s_cmp_eq_u32 s75, 28
	s_cselect_b32 s45, s15, s43
	s_cselect_b32 s44, s71, s42
	s_cselect_b32 s43, s13, s74
	s_cselect_b32 s42, s72, s73
	s_add_i32 s79, 0, 0x14000
	s_add_i32 m0, s53, 0xc000
	s_nop 0
	global_load_lds_dwordx4 v138, s[20:21]
	ds_read_b128 v[158:161], v144
	ds_read_b128 v[162:165], v144 offset:1024
	ds_read_b128 v[166:169], v144 offset:2048
	ds_read_b128 v[170:173], v144 offset:3072
	ds_read_b128 v[174:177], v144 offset:16384
	ds_read_b128 v[178:181], v144 offset:17408
	ds_read_b128 v[182:185], v144 offset:18432
	ds_read_b128 v[186:189], v144 offset:19456
	s_add_i32 m0, s53, 0xe000
	s_nop 0
	global_load_lds_dwordx4 v140, s[20:21]
	ds_read_b128 v[190:193], v155
	ds_read_b128 v[206:209], v155 offset:1024
	ds_read_b128 v[210:213], v155 offset:2048
	ds_read_b128 v[214:217], v155 offset:3072
	ds_read_b128 v[226:229], v155 offset:4096
	ds_read_b128 v[234:237], v155 offset:5120
	ds_read_b128 v[238:241], v155 offset:6144
	ds_read_b128 v[242:245], v155 offset:7168
	s_waitcnt vmcnt(8)
	s_waitcnt lgkmcnt(0)
	s_barrier
	s_setprio 1
	s_waitcnt lgkmcnt(0)
	v_mfma_f32_16x16x32_bf16 v[126:129], v[158:161], v[190:193], v[126:129]
	v_mfma_f32_16x16x32_bf16 v[118:121], v[166:169], v[190:193], v[118:121]
	v_mfma_f32_16x16x32_bf16 v[102:105], v[166:169], v[210:213], v[102:105]
	v_mfma_f32_16x16x32_bf16 v[110:113], v[158:161], v[210:213], v[110:113]
	v_mfma_f32_16x16x32_bf16 v[94:97], v[158:161], v[226:229], v[94:97]
	v_mfma_f32_16x16x32_bf16 v[86:89], v[166:169], v[226:229], v[86:89]
	v_mfma_f32_16x16x32_bf16 v[70:73], v[166:169], v[238:241], v[70:73]
	v_mfma_f32_16x16x32_bf16 v[78:81], v[158:161], v[238:241], v[78:81]
	v_mfma_f32_16x16x32_bf16 v[126:129], v[162:165], v[206:209], v[126:129]
	v_mfma_f32_16x16x32_bf16 v[118:121], v[170:173], v[206:209], v[118:121]
	v_mfma_f32_16x16x32_bf16 v[102:105], v[170:173], v[214:217], v[102:105]
	v_mfma_f32_16x16x32_bf16 v[110:113], v[162:165], v[214:217], v[110:113]
	v_mfma_f32_16x16x32_bf16 v[94:97], v[162:165], v[234:237], v[94:97]
	v_mfma_f32_16x16x32_bf16 v[86:89], v[170:173], v[234:237], v[86:89]
	v_mfma_f32_16x16x32_bf16 v[70:73], v[170:173], v[242:245], v[70:73]
	v_mfma_f32_16x16x32_bf16 v[78:81], v[162:165], v[242:245], v[78:81]
	s_setprio 0
	s_setprio 1
	v_mfma_f32_16x16x32_bf16 v[122:125], v[174:177], v[190:193], v[122:125]
	v_mfma_f32_16x16x32_bf16 v[114:117], v[182:185], v[190:193], v[114:117]
	v_mfma_f32_16x16x32_bf16 v[98:101], v[182:185], v[210:213], v[98:101]
	v_mfma_f32_16x16x32_bf16 v[106:109], v[174:177], v[210:213], v[106:109]
	v_mfma_f32_16x16x32_bf16 v[90:93], v[174:177], v[226:229], v[90:93]
	v_mfma_f32_16x16x32_bf16 v[82:85], v[182:185], v[226:229], v[82:85]
	v_mfma_f32_16x16x32_bf16 v[66:69], v[182:185], v[238:241], v[66:69]
	v_mfma_f32_16x16x32_bf16 v[74:77], v[174:177], v[238:241], v[74:77]
	v_mfma_f32_16x16x32_bf16 v[122:125], v[178:181], v[206:209], v[122:125]
	v_mfma_f32_16x16x32_bf16 v[114:117], v[186:189], v[206:209], v[114:117]
	v_mfma_f32_16x16x32_bf16 v[98:101], v[186:189], v[214:217], v[98:101]
	v_mfma_f32_16x16x32_bf16 v[106:109], v[178:181], v[214:217], v[106:109]
	v_mfma_f32_16x16x32_bf16 v[90:93], v[178:181], v[234:237], v[90:93]
	v_mfma_f32_16x16x32_bf16 v[82:85], v[186:189], v[234:237], v[82:85]
	v_mfma_f32_16x16x32_bf16 v[66:69], v[186:189], v[242:245], v[66:69]
	v_mfma_f32_16x16x32_bf16 v[74:77], v[178:181], v[242:245], v[74:77]
	s_setprio 0
	s_barrier
	s_add_i32 s76, s76, s41
	s_mov_b32 m0, s76
	s_nop 0
	global_load_lds_dwordx4 v132, s[42:43]
	ds_read_b128 v[190:193], v155 offset:16384
	ds_read_b128 v[206:209], v155 offset:17408
	s_add_i32 m0, s76, 0x2000
	s_add_u32 s76, s42, 0x80000
	s_addc_u32 s77, s43, 0
	s_add_i32 s79, s79, s41
	global_load_lds_dwordx4 v136, s[42:43]
	ds_read_b128 v[210:213], v155 offset:18432
	ds_read_b128 v[214:217], v155 offset:19456
	s_mov_b32 m0, s79
	s_nop 0
	global_load_lds_dwordx4 v132, s[76:77]
	ds_read_b128 v[226:229], v155 offset:20480
	ds_read_b128 v[234:237], v155 offset:21504
	s_add_i32 m0, s79, 0x2000
	s_nop 0
	global_load_lds_dwordx4 v136, s[76:77]
	ds_read_b128 v[238:241], v155 offset:22528
	ds_read_b128 v[242:245], v155 offset:23552
	s_mov_b32 m0, s53
	s_nop 0
	global_load_lds_dwordx4 v130, s[44:45]
	s_mov_b32 m0, s56
	s_nop 0
	global_load_lds_dwordx4 v134, s[44:45]
	s_waitcnt vmcnt(8)
	s_waitcnt lgkmcnt(0)
	s_barrier
	s_setprio 1
	s_waitcnt lgkmcnt(0)
	v_mfma_f32_16x16x32_bf16 v[62:65], v[158:161], v[190:193], v[62:65]
	v_mfma_f32_16x16x32_bf16 v[54:57], v[166:169], v[190:193], v[54:57]
	v_mfma_f32_16x16x32_bf16 v[38:41], v[166:169], v[210:213], v[38:41]
	v_mfma_f32_16x16x32_bf16 v[46:49], v[158:161], v[210:213], v[46:49]
	v_mfma_f32_16x16x32_bf16 v[30:33], v[158:161], v[226:229], v[30:33]
	v_mfma_f32_16x16x32_bf16 v[22:25], v[166:169], v[226:229], v[22:25]
	v_mfma_f32_16x16x32_bf16 v[6:9], v[166:169], v[238:241], v[6:9]
	v_mfma_f32_16x16x32_bf16 v[14:17], v[158:161], v[238:241], v[14:17]
	v_mfma_f32_16x16x32_bf16 v[62:65], v[162:165], v[206:209], v[62:65]
	v_mfma_f32_16x16x32_bf16 v[54:57], v[170:173], v[206:209], v[54:57]
	v_mfma_f32_16x16x32_bf16 v[38:41], v[170:173], v[214:217], v[38:41]
	v_mfma_f32_16x16x32_bf16 v[46:49], v[162:165], v[214:217], v[46:49]
	v_mfma_f32_16x16x32_bf16 v[30:33], v[162:165], v[234:237], v[30:33]
	v_mfma_f32_16x16x32_bf16 v[22:25], v[170:173], v[234:237], v[22:25]
	v_mfma_f32_16x16x32_bf16 v[6:9], v[170:173], v[242:245], v[6:9]
	v_mfma_f32_16x16x32_bf16 v[14:17], v[162:165], v[242:245], v[14:17]
	s_setprio 0
	s_setprio 1
	v_mfma_f32_16x16x32_bf16 v[58:61], v[174:177], v[190:193], v[58:61]
	v_mfma_f32_16x16x32_bf16 v[50:53], v[182:185], v[190:193], v[50:53]
	v_mfma_f32_16x16x32_bf16 v[34:37], v[182:185], v[210:213], v[34:37]
	v_mfma_f32_16x16x32_bf16 v[42:45], v[174:177], v[210:213], v[42:45]
	v_mfma_f32_16x16x32_bf16 v[26:29], v[174:177], v[226:229], v[26:29]
	v_mfma_f32_16x16x32_bf16 v[18:21], v[182:185], v[226:229], v[18:21]
	v_mfma_f32_16x16x32_bf16 v[2:5], v[182:185], v[238:241], v[2:5]
	v_mfma_f32_16x16x32_bf16 v[10:13], v[174:177], v[238:241], v[10:13]
	v_mfma_f32_16x16x32_bf16 v[58:61], v[178:181], v[206:209], v[58:61]
	v_mfma_f32_16x16x32_bf16 v[50:53], v[186:189], v[206:209], v[50:53]
	v_mfma_f32_16x16x32_bf16 v[34:37], v[186:189], v[214:217], v[34:37]
	v_mfma_f32_16x16x32_bf16 v[42:45], v[178:181], v[214:217], v[42:45]
	v_mfma_f32_16x16x32_bf16 v[26:29], v[178:181], v[234:237], v[26:29]
	v_mfma_f32_16x16x32_bf16 v[18:21], v[186:189], v[234:237], v[18:21]
	v_mfma_f32_16x16x32_bf16 v[2:5], v[186:189], v[242:245], v[2:5]
	v_mfma_f32_16x16x32_bf16 v[10:13], v[178:181], v[242:245], v[10:13]
	s_setprio 0
	s_barrier
; #define PG8_STAGE(bufoff, gbase, voff) do { _Pragma("unroll") for (int _i = 0; _i < 2; ++_i) \
;         __builtin_amdgcn_global_load_lds((const unsigned*)((const char*)(gbase) + (voff)[_i]), (PG8_LAS unsigned*)(lds + (bufoff) + ldsw + _i * 8192), 16, 0, 0); } while (0)
; #define PG8_LDA(dst, b, h) do { _Pragma("unroll") for (int m = 0; m < 4; ++m) _Pragma("unroll") for (int k = 0; k < 2; ++k) dst[m][k] = *(const PG8_LAS bf16x8*)(lds + PG8_SA(b, h) + aoff + m * 2048 + k * 1024); } while (0)
; #define PG8_LDB(dst, b, h) do { _Pragma("unroll") for (int n = 0; n < 2; ++n) _Pragma("unroll") for (int k = 0; k < 2; ++k) dst[n][k] = *(const PG8_LAS bf16x8*)(lds + PG8_SB(b, h) + boff + n * 2048 + k * 1024); } while (0)
; #define PG8_MMA(ai, bj, At, Bt) do { __builtin_amdgcn_s_setprio(1); _Pragma("unroll") for (int m = 0; m < 4; ++m) _Pragma("unroll") for (int n = 0; n < 2; ++n) _Pragma("unroll") for (int k = 0; k < 2; ++k) \
;         acc[ai][bj][m][n] = __builtin_amdgcn_mfma_f32_16x16x32_bf16(Bt[n][k], At[m][k], acc[ai][bj][m][n], 0, 0, 0); __builtin_amdgcn_s_setprio(0); } while (0)
; #define PG8_WAIT_V(n) asm volatile("s_waitcnt vmcnt(" #n ")" ::: "memory")
; #define PG8_WAIT_L(n) asm volatile("s_waitcnt lgkmcnt(" #n ")" ::: "memory")
; #define PG8_BAR __builtin_amdgcn_s_barrier()
; #define PG8_SCHED __builtin_amdgcn_sched_barrier(0)
; template <class Epi, class Sched, bool ALIGN_EPI = false, bool SP2 = false>
; __device__ __forceinline__ void gemm_phase(PG8_LAS unsigned char* lds, const Gemm g, const Sched& S, const Epi& E, const int wave_id) {
;     ...
;             PG8_LDB(B0, 1, 0); PG8_LDB(B1, 1, 1); PG8_SCHED; PG8_LDA(At, 1, 0); PG8_STAGE(PG8_SA(0, 1), a2 + hstep, voffA);
;             PG8_WAIT_V(8); PG8_WAIT_L(0); PG8_BAR; PG8_MMA(0, 0, At, B0); PG8_MMA(0, 1, At, B1); PG8_BAR; PG8_SCHED;
;             PG8_LDA(At, 1, 1); PG8_STAGE(PG8_SB(1, 0), b3, voffB); PG8_STAGE(PG8_SB(1, 1), b3 + hstep, voffB); PG8_STAGE(PG8_SA(1, 0), a3, voffA);
;             PG8_WAIT_V(8); PG8_WAIT_L(0); PG8_BAR; PG8_MMA(1, 0, At, B0); PG8_MMA(1, 1, At, B1); PG8_BAR; PG8_SCHED;
;     ...
;         if constexpr (ALIGN_EPI) { if (wr == 0) PG8_BAR; }
	s_add_i32 s76, 0, 0x18000
	s_add_i32 s77, 0, 0x1c000
	s_add_u32 s44, s44, 0x80000
	s_addc_u32 s45, s45, 0
	s_mov_b32 m0, s57
	s_nop 0
	global_load_lds_dwordx4 v130, s[44:45]
	ds_read_b128 v[158:161], v144 offset:32768
	ds_read_b128 v[162:165], v144 offset:33792
	ds_read_b128 v[166:169], v144 offset:34816
	ds_read_b128 v[170:173], v144 offset:35840
	ds_read_b128 v[174:177], v144 offset:49152
	ds_read_b128 v[178:181], v144 offset:50176
	ds_read_b128 v[182:185], v144 offset:51200
	ds_read_b128 v[186:189], v144 offset:52224
	s_mov_b32 m0, s64
	s_nop 0
	global_load_lds_dwordx4 v134, s[44:45]
	ds_read_b128 v[190:193], v155 offset:32768
	ds_read_b128 v[206:209], v155 offset:33792
	ds_read_b128 v[210:213], v155 offset:34816
	ds_read_b128 v[214:217], v155 offset:35840
	ds_read_b128 v[226:229], v155 offset:36864
	ds_read_b128 v[234:237], v155 offset:37888
	ds_read_b128 v[238:241], v155 offset:38912
	ds_read_b128 v[242:245], v155 offset:39936
	s_waitcnt vmcnt(8)
	s_waitcnt lgkmcnt(0)
	s_barrier
	s_setprio 1
	s_waitcnt lgkmcnt(0)
	v_mfma_f32_16x16x32_bf16 v[126:129], v[158:161], v[190:193], v[126:129]
	v_mfma_f32_16x16x32_bf16 v[118:121], v[166:169], v[190:193], v[118:121]
	v_mfma_f32_16x16x32_bf16 v[102:105], v[166:169], v[210:213], v[102:105]
	v_mfma_f32_16x16x32_bf16 v[110:113], v[158:161], v[210:213], v[110:113]
	v_mfma_f32_16x16x32_bf16 v[94:97], v[158:161], v[226:229], v[94:97]
	v_mfma_f32_16x16x32_bf16 v[86:89], v[166:169], v[226:229], v[86:89]
	v_mfma_f32_16x16x32_bf16 v[70:73], v[166:169], v[238:241], v[70:73]
	v_mfma_f32_16x16x32_bf16 v[78:81], v[158:161], v[238:241], v[78:81]
	v_mfma_f32_16x16x32_bf16 v[126:129], v[162:165], v[206:209], v[126:129]
	v_mfma_f32_16x16x32_bf16 v[118:121], v[170:173], v[206:209], v[118:121]
	v_mfma_f32_16x16x32_bf16 v[102:105], v[170:173], v[214:217], v[102:105]
	v_mfma_f32_16x16x32_bf16 v[110:113], v[162:165], v[214:217], v[110:113]
	v_mfma_f32_16x16x32_bf16 v[94:97], v[162:165], v[234:237], v[94:97]
	v_mfma_f32_16x16x32_bf16 v[86:89], v[170:173], v[234:237], v[86:89]
	v_mfma_f32_16x16x32_bf16 v[70:73], v[170:173], v[242:245], v[70:73]
	v_mfma_f32_16x16x32_bf16 v[78:81], v[162:165], v[242:245], v[78:81]
	s_setprio 0
	s_setprio 1
	v_mfma_f32_16x16x32_bf16 v[122:125], v[174:177], v[190:193], v[122:125]
	v_mfma_f32_16x16x32_bf16 v[114:117], v[182:185], v[190:193], v[114:117]
	v_mfma_f32_16x16x32_bf16 v[98:101], v[182:185], v[210:213], v[98:101]
	v_mfma_f32_16x16x32_bf16 v[106:109], v[174:177], v[210:213], v[106:109]
	v_mfma_f32_16x16x32_bf16 v[90:93], v[174:177], v[226:229], v[90:93]
	v_mfma_f32_16x16x32_bf16 v[82:85], v[182:185], v[226:229], v[82:85]
	v_mfma_f32_16x16x32_bf16 v[66:69], v[182:185], v[238:241], v[66:69]
	v_mfma_f32_16x16x32_bf16 v[74:77], v[174:177], v[238:241], v[74:77]
	v_mfma_f32_16x16x32_bf16 v[122:125], v[178:181], v[206:209], v[122:125]
	v_mfma_f32_16x16x32_bf16 v[114:117], v[186:189], v[206:209], v[114:117]
	v_mfma_f32_16x16x32_bf16 v[98:101], v[186:189], v[214:217], v[98:101]
	v_mfma_f32_16x16x32_bf16 v[106:109], v[178:181], v[214:217], v[106:109]
	v_mfma_f32_16x16x32_bf16 v[90:93], v[178:181], v[234:237], v[90:93]
	v_mfma_f32_16x16x32_bf16 v[82:85], v[186:189], v[234:237], v[82:85]
	v_mfma_f32_16x16x32_bf16 v[66:69], v[186:189], v[242:245], v[66:69]
	v_mfma_f32_16x16x32_bf16 v[74:77], v[178:181], v[242:245], v[74:77]
	s_setprio 0
	s_barrier
	s_add_u32 vcc_lo, s44, 0xfff80080
	s_addc_u32 vcc_hi, s45, -1
	s_mov_b32 m0, s65
	s_nop 0
	global_load_lds_dwordx4 v130, vcc
	ds_read_b128 v[190:193], v155 offset:49152
	ds_read_b128 v[206:209], v155 offset:50176
	s_mov_b32 m0, s68
	s_add_i32 s44, s76, s41
	global_load_lds_dwordx4 v134, vcc
	ds_read_b128 v[210:213], v155 offset:51200
	ds_read_b128 v[214:217], v155 offset:52224
	s_add_u32 vcc_lo, s42, 0x80
	s_addc_u32 vcc_hi, s43, 0
	s_mov_b32 m0, s44
	s_nop 0
	global_load_lds_dwordx4 v132, vcc
	ds_read_b128 v[226:229], v155 offset:53248
	ds_read_b128 v[234:237], v155 offset:54272
	s_add_i32 m0, s44, 0x2000
	s_add_u32 s42, s42, 0x80080
	s_addc_u32 s43, s43, 0
	global_load_lds_dwordx4 v136, vcc
	ds_read_b128 v[238:241], v155 offset:55296
	ds_read_b128 v[242:245], v155 offset:56320
	s_add_i32 s44, s77, s41
	s_mov_b32 m0, s44
	s_nop 0
	global_load_lds_dwordx4 v132, s[42:43]
	s_add_i32 m0, s44, 0x2000
	s_nop 0
	global_load_lds_dwordx4 v136, s[42:43]
	s_waitcnt vmcnt(8)
	s_waitcnt lgkmcnt(0)
	s_barrier
	s_setprio 1
	s_waitcnt lgkmcnt(0)
	v_mfma_f32_16x16x32_bf16 v[62:65], v[158:161], v[190:193], v[62:65]
	v_mfma_f32_16x16x32_bf16 v[54:57], v[166:169], v[190:193], v[54:57]
	v_mfma_f32_16x16x32_bf16 v[38:41], v[166:169], v[210:213], v[38:41]
	v_mfma_f32_16x16x32_bf16 v[46:49], v[158:161], v[210:213], v[46:49]
	v_mfma_f32_16x16x32_bf16 v[30:33], v[158:161], v[226:229], v[30:33]
	v_mfma_f32_16x16x32_bf16 v[22:25], v[166:169], v[226:229], v[22:25]
	v_mfma_f32_16x16x32_bf16 v[6:9], v[166:169], v[238:241], v[6:9]
	v_mfma_f32_16x16x32_bf16 v[14:17], v[158:161], v[238:241], v[14:17]
	v_mfma_f32_16x16x32_bf16 v[62:65], v[162:165], v[206:209], v[62:65]
	v_mfma_f32_16x16x32_bf16 v[54:57], v[170:173], v[206:209], v[54:57]
	v_mfma_f32_16x16x32_bf16 v[38:41], v[170:173], v[214:217], v[38:41]
	v_mfma_f32_16x16x32_bf16 v[46:49], v[162:165], v[214:217], v[46:49]
	v_mfma_f32_16x16x32_bf16 v[30:33], v[162:165], v[234:237], v[30:33]
	v_mfma_f32_16x16x32_bf16 v[22:25], v[170:173], v[234:237], v[22:25]
	v_mfma_f32_16x16x32_bf16 v[6:9], v[170:173], v[242:245], v[6:9]
	v_mfma_f32_16x16x32_bf16 v[14:17], v[162:165], v[242:245], v[14:17]
	s_setprio 0
	s_setprio 1
	v_mfma_f32_16x16x32_bf16 v[58:61], v[174:177], v[190:193], v[58:61]
	v_mfma_f32_16x16x32_bf16 v[50:53], v[182:185], v[190:193], v[50:53]
	v_mfma_f32_16x16x32_bf16 v[34:37], v[182:185], v[210:213], v[34:37]
	v_mfma_f32_16x16x32_bf16 v[42:45], v[174:177], v[210:213], v[42:45]
	v_mfma_f32_16x16x32_bf16 v[26:29], v[174:177], v[226:229], v[26:29]
	v_mfma_f32_16x16x32_bf16 v[18:21], v[182:185], v[226:229], v[18:21]
	v_mfma_f32_16x16x32_bf16 v[2:5], v[182:185], v[238:241], v[2:5]
	v_mfma_f32_16x16x32_bf16 v[10:13], v[174:177], v[238:241], v[10:13]
	v_mfma_f32_16x16x32_bf16 v[58:61], v[178:181], v[206:209], v[58:61]
	v_mfma_f32_16x16x32_bf16 v[50:53], v[186:189], v[206:209], v[50:53]
	v_mfma_f32_16x16x32_bf16 v[34:37], v[186:189], v[214:217], v[34:37]
	v_mfma_f32_16x16x32_bf16 v[42:45], v[178:181], v[214:217], v[42:45]
	v_mfma_f32_16x16x32_bf16 v[26:29], v[178:181], v[234:237], v[26:29]
	v_mfma_f32_16x16x32_bf16 v[18:21], v[186:189], v[234:237], v[18:21]
	v_mfma_f32_16x16x32_bf16 v[2:5], v[186:189], v[242:245], v[2:5]
	v_mfma_f32_16x16x32_bf16 v[10:13], v[178:181], v[242:245], v[10:13]
	s_setprio 0
	s_barrier
	s_add_i32 s75, s75, 2
	s_add_u32 s20, s20, 0x100
	s_addc_u32 s21, s21, 0
	s_add_u32 s73, s73, 0x100
	s_addc_u32 s74, s74, 0
	s_cmp_gt_u32 s75, 29
	s_cbranch_scc0 .LBB0_641
	s_and_b64 vcc, exec, s[10:11]
	s_cbranch_vccz .LBB0_644
	s_barrier

; #define PG8_STAGE(bufoff, gbase, voff) do { _Pragma("unroll") for (int _i = 0; _i < 2; ++_i) \
;         __builtin_amdgcn_global_load_lds((const unsigned*)((const char*)(gbase) + (voff)[_i]), (PG8_LAS unsigned*)(lds + (bufoff) + ldsw + _i * 8192), 16, 0, 0); } while (0)
; #define PG8_LDA(dst, b, h) do { _Pragma("unroll") for (int m = 0; m < 4; ++m) _Pragma("unroll") for (int k = 0; k < 2; ++k) dst[m][k] = *(const PG8_LAS bf16x8*)(lds + PG8_SA(b, h) + aoff + m * 2048 + k * 1024); } while (0)
; #define PG8_LDB(dst, b, h) do { _Pragma("unroll") for (int n = 0; n < 2; ++n) _Pragma("unroll") for (int k = 0; k < 2; ++k) dst[n][k] = *(const PG8_LAS bf16x8*)(lds + PG8_SB(b, h) + boff + n * 2048 + k * 1024); } while (0)
; #define PG8_MMA(ai, bj, At, Bt) do { __builtin_amdgcn_s_setprio(1); _Pragma("unroll") for (int m = 0; m < 4; ++m) _Pragma("unroll") for (int n = 0; n < 2; ++n) _Pragma("unroll") for (int k = 0; k < 2; ++k) \
;         acc[ai][bj][m][n] = __builtin_amdgcn_mfma_f32_16x16x32_bf16(Bt[n][k], At[m][k], acc[ai][bj][m][n], 0, 0, 0); __builtin_amdgcn_s_setprio(0); } while (0)
; #define PG8_WAIT_V(n) asm volatile("s_waitcnt vmcnt(" #n ")" ::: "memory")
; #define PG8_WAIT_L(n) asm volatile("s_waitcnt lgkmcnt(" #n ")" ::: "memory")
; template <class Epi, class Sched, bool ALIGN_EPI = false, bool SP2 = false>
; __device__ __forceinline__ void gemm_phase(PG8_LAS unsigned char* lds, const Gemm g, const Sched& S, const Epi& E, const int wave_id) {
;     ...
;             const bool last = (t == nt - 2);
;             const char* a1 = cA + (size_t)(t + 1) * kstep;
;             const char* a2 = last ? nA : cA + (size_t)(t + 2) * kstep; const char* b2 = last ? nB : cB + (size_t)(t + 2) * kstep;
;             const char* a3 = a2 + kstep; const char* b3 = b2 + kstep;
;             if (last && has_next) S.a_ready(nxt);
;             if constexpr (SP2) {
;             PG8_LDB(B0, 0, 0); PG8_LDB(B1, 0, 1); PG8_SCHED; PG8_LDA(At, 0, 0); PG8_STAGE(PG8_SA(1, 1), a1 + hstep, voffA);
;             PG8_WAIT_V(8); PG8_WAIT_L(0); PG8_BAR; PG8_MMA(0, 0, At, B0); PG8_MMA(0, 1, At, B1); PG8_BAR; PG8_SCHED;
;             PG8_LDA(At, 0, 1); PG8_STAGE(PG8_SB(0, 0), b2, voffB); PG8_STAGE(PG8_SB(0, 1), b2 + hstep, voffB); PG8_STAGE(PG8_SA(0, 0), a2, voffA);
;             PG8_WAIT_V(8); PG8_WAIT_L(0); PG8_BAR; PG8_MMA(1, 0, At, B0); PG8_MMA(1, 1, At, B1); PG8_BAR; PG8_SCHED;
.LBB0_759:
	s_add_u32 s20, s18, 0x100
	s_addc_u32 s21, s19, 0
	s_add_i32 s77, 0, 0x10000
	s_cmpk_eq_i32 s76, 0x54
	s_cselect_b32 s43, s15, s21
	s_cselect_b32 s42, s14, s20
	s_cselect_b32 s41, s17, s75
	s_cselect_b32 s40, s16, s74
	s_add_i32 s79, 0, 0x14000
	s_add_i32 m0, s52, 0xc000
	s_nop 0
	global_load_lds_dwordx4 v210, s[18:19]
	ds_read_b128 v[118:121], v226
	ds_read_b128 v[122:125], v226 offset:1024
	ds_read_b128 v[130:133], v226 offset:2048
	ds_read_b128 v[134:137], v226 offset:3072
	ds_read_b128 v[146:149], v226 offset:16384
	ds_read_b128 v[150:153], v226 offset:17408
	ds_read_b128 v[154:157], v226 offset:18432
	ds_read_b128 v[158:161], v226 offset:19456
	s_add_i32 m0, s52, 0xe000
	s_nop 0
	global_load_lds_dwordx4 v212, s[18:19]
	ds_read_b128 v[162:165], v222
	ds_read_b128 v[166:169], v222 offset:1024
	ds_read_b128 v[170:173], v222 offset:2048
	ds_read_b128 v[174:177], v222 offset:3072
	ds_read_b128 v[178:181], v222 offset:4096
	ds_read_b128 v[182:185], v222 offset:5120
	ds_read_b128 v[186:189], v222 offset:6144
	ds_read_b128 v[214:217], v222 offset:7168
	s_waitcnt vmcnt(8)
	s_waitcnt lgkmcnt(0)
	s_barrier
	s_setprio 1
	s_waitcnt lgkmcnt(0)
	v_mfma_f32_16x16x32_bf16 v[142:145], v[118:121], v[162:165], v[142:145]
	v_mfma_f32_16x16x32_bf16 v[138:141], v[130:133], v[162:165], v[138:141]
	v_mfma_f32_16x16x32_bf16 v[106:109], v[130:133], v[170:173], v[106:109]
	v_mfma_f32_16x16x32_bf16 v[110:113], v[118:121], v[170:173], v[110:113]
	v_mfma_f32_16x16x32_bf16 v[94:97], v[118:121], v[178:181], v[94:97]
	v_mfma_f32_16x16x32_bf16 v[90:93], v[130:133], v[178:181], v[90:93]
	v_mfma_f32_16x16x32_bf16 v[74:77], v[130:133], v[186:189], v[74:77]
	v_mfma_f32_16x16x32_bf16 v[78:81], v[118:121], v[186:189], v[78:81]
	v_mfma_f32_16x16x32_bf16 v[142:145], v[122:125], v[166:169], v[142:145]
	v_mfma_f32_16x16x32_bf16 v[138:141], v[134:137], v[166:169], v[138:141]
	v_mfma_f32_16x16x32_bf16 v[106:109], v[134:137], v[174:177], v[106:109]
	v_mfma_f32_16x16x32_bf16 v[110:113], v[122:125], v[174:177], v[110:113]
	v_mfma_f32_16x16x32_bf16 v[94:97], v[122:125], v[182:185], v[94:97]
	v_mfma_f32_16x16x32_bf16 v[90:93], v[134:137], v[182:185], v[90:93]
	v_mfma_f32_16x16x32_bf16 v[74:77], v[134:137], v[214:217], v[74:77]
	v_mfma_f32_16x16x32_bf16 v[78:81], v[122:125], v[214:217], v[78:81]
	s_setprio 0
	s_setprio 1
	v_mfma_f32_16x16x32_bf16 v[126:129], v[146:149], v[162:165], v[126:129]
	v_mfma_f32_16x16x32_bf16 v[114:117], v[154:157], v[162:165], v[114:117]
	v_mfma_f32_16x16x32_bf16 v[98:101], v[154:157], v[170:173], v[98:101]
	v_mfma_f32_16x16x32_bf16 v[102:105], v[146:149], v[170:173], v[102:105]
	v_mfma_f32_16x16x32_bf16 v[86:89], v[146:149], v[178:181], v[86:89]
	v_mfma_f32_16x16x32_bf16 v[82:85], v[154:157], v[178:181], v[82:85]
	v_mfma_f32_16x16x32_bf16 v[66:69], v[154:157], v[186:189], v[66:69]
	v_mfma_f32_16x16x32_bf16 v[70:73], v[146:149], v[186:189], v[70:73]
	v_mfma_f32_16x16x32_bf16 v[126:129], v[150:153], v[166:169], v[126:129]
	v_mfma_f32_16x16x32_bf16 v[114:117], v[158:161], v[166:169], v[114:117]
	v_mfma_f32_16x16x32_bf16 v[98:101], v[158:161], v[174:177], v[98:101]
	v_mfma_f32_16x16x32_bf16 v[102:105], v[150:153], v[174:177], v[102:105]
	v_mfma_f32_16x16x32_bf16 v[86:89], v[150:153], v[182:185], v[86:89]
	v_mfma_f32_16x16x32_bf16 v[82:85], v[158:161], v[182:185], v[82:85]
	v_mfma_f32_16x16x32_bf16 v[66:69], v[158:161], v[214:217], v[66:69]
	v_mfma_f32_16x16x32_bf16 v[70:73], v[150:153], v[214:217], v[70:73]
	s_setprio 0
	s_barrier
	s_add_i32 s18, s77, s49
	s_mov_b32 m0, s18
	s_nop 0
	global_load_lds_dwordx4 v192, s[40:41]
	ds_read_b128 v[162:165], v222 offset:16384
	ds_read_b128 v[166:169], v222 offset:17408
	s_add_i32 m0, s18, 0x2000
	s_add_u32 s18, s40, 0x160000
	s_addc_u32 s19, s41, 0
	s_add_i32 s77, s79, s49
	global_load_lds_dwordx4 v208, s[40:41]
	ds_read_b128 v[170:173], v222 offset:18432
	ds_read_b128 v[174:177], v222 offset:19456
	s_mov_b32 m0, s77
	s_nop 0
	global_load_lds_dwordx4 v192, s[18:19]
	ds_read_b128 v[178:181], v222 offset:20480
	ds_read_b128 v[182:185], v222 offset:21504
	s_add_i32 m0, s77, 0x2000
	s_nop 0
	global_load_lds_dwordx4 v208, s[18:19]
	ds_read_b128 v[186:189], v222 offset:22528
	ds_read_b128 v[214:217], v222 offset:23552
	s_mov_b32 m0, s52
	s_nop 0
	global_load_lds_dwordx4 v190, s[42:43]
	s_mov_b32 m0, s53
	s_nop 0
	global_load_lds_dwordx4 v206, s[42:43]
	s_waitcnt vmcnt(8)
	s_waitcnt lgkmcnt(0)
	s_barrier
	s_setprio 1
	s_waitcnt lgkmcnt(0)
	v_mfma_f32_16x16x32_bf16 v[62:65], v[118:121], v[162:165], v[62:65]
	v_mfma_f32_16x16x32_bf16 v[58:61], v[130:133], v[162:165], v[58:61]
	v_mfma_f32_16x16x32_bf16 v[42:45], v[130:133], v[170:173], v[42:45]
	v_mfma_f32_16x16x32_bf16 v[46:49], v[118:121], v[170:173], v[46:49]
	v_mfma_f32_16x16x32_bf16 v[30:33], v[118:121], v[178:181], v[30:33]
	v_mfma_f32_16x16x32_bf16 v[26:29], v[130:133], v[178:181], v[26:29]
	v_mfma_f32_16x16x32_bf16 v[10:13], v[130:133], v[186:189], v[10:13]
	v_mfma_f32_16x16x32_bf16 v[14:17], v[118:121], v[186:189], v[14:17]
	v_mfma_f32_16x16x32_bf16 v[62:65], v[122:125], v[166:169], v[62:65]
	v_mfma_f32_16x16x32_bf16 v[58:61], v[134:137], v[166:169], v[58:61]
	v_mfma_f32_16x16x32_bf16 v[42:45], v[134:137], v[174:177], v[42:45]
	v_mfma_f32_16x16x32_bf16 v[46:49], v[122:125], v[174:177], v[46:49]
	v_mfma_f32_16x16x32_bf16 v[30:33], v[122:125], v[182:185], v[30:33]
	v_mfma_f32_16x16x32_bf16 v[26:29], v[134:137], v[182:185], v[26:29]
	v_mfma_f32_16x16x32_bf16 v[10:13], v[134:137], v[214:217], v[10:13]
	v_mfma_f32_16x16x32_bf16 v[14:17], v[122:125], v[214:217], v[14:17]
	s_setprio 0
	s_setprio 1
	v_mfma_f32_16x16x32_bf16 v[54:57], v[146:149], v[162:165], v[54:57]
	v_mfma_f32_16x16x32_bf16 v[50:53], v[154:157], v[162:165], v[50:53]
	v_mfma_f32_16x16x32_bf16 v[34:37], v[154:157], v[170:173], v[34:37]
	v_mfma_f32_16x16x32_bf16 v[38:41], v[146:149], v[170:173], v[38:41]
	v_mfma_f32_16x16x32_bf16 v[22:25], v[146:149], v[178:181], v[22:25]
	v_mfma_f32_16x16x32_bf16 v[18:21], v[154:157], v[178:181], v[18:21]
	v_mfma_f32_16x16x32_bf16 v[2:5], v[154:157], v[186:189], v[2:5]
	v_mfma_f32_16x16x32_bf16 v[6:9], v[146:149], v[186:189], v[6:9]
	v_mfma_f32_16x16x32_bf16 v[54:57], v[150:153], v[166:169], v[54:57]
	v_mfma_f32_16x16x32_bf16 v[50:53], v[158:161], v[166:169], v[50:53]
	v_mfma_f32_16x16x32_bf16 v[34:37], v[158:161], v[174:177], v[34:37]
	v_mfma_f32_16x16x32_bf16 v[38:41], v[150:153], v[174:177], v[38:41]
	v_mfma_f32_16x16x32_bf16 v[22:25], v[150:153], v[182:185], v[22:25]
	v_mfma_f32_16x16x32_bf16 v[18:21], v[158:161], v[182:185], v[18:21]
	v_mfma_f32_16x16x32_bf16 v[2:5], v[158:161], v[214:217], v[2:5]
	v_mfma_f32_16x16x32_bf16 v[6:9], v[150:153], v[214:217], v[6:9]
	s_setprio 0
	s_barrier
; #define PG8_STAGE(bufoff, gbase, voff) do { _Pragma("unroll") for (int _i = 0; _i < 2; ++_i) \
;         __builtin_amdgcn_global_load_lds((const unsigned*)((const char*)(gbase) + (voff)[_i]), (PG8_LAS unsigned*)(lds + (bufoff) + ldsw + _i * 8192), 16, 0, 0); } while (0)
; #define PG8_LDA(dst, b, h) do { _Pragma("unroll") for (int m = 0; m < 4; ++m) _Pragma("unroll") for (int k = 0; k < 2; ++k) dst[m][k] = *(const PG8_LAS bf16x8*)(lds + PG8_SA(b, h) + aoff + m * 2048 + k * 1024); } while (0)
; #define PG8_LDB(dst, b, h) do { _Pragma("unroll") for (int n = 0; n < 2; ++n) _Pragma("unroll") for (int k = 0; k < 2; ++k) dst[n][k] = *(const PG8_LAS bf16x8*)(lds + PG8_SB(b, h) + boff + n * 2048 + k * 1024); } while (0)
; #define PG8_MMA(ai, bj, At, Bt) do { __builtin_amdgcn_s_setprio(1); _Pragma("unroll") for (int m = 0; m < 4; ++m) _Pragma("unroll") for (int n = 0; n < 2; ++n) _Pragma("unroll") for (int k = 0; k < 2; ++k) \
;         acc[ai][bj][m][n] = __builtin_amdgcn_mfma_f32_16x16x32_bf16(Bt[n][k], At[m][k], acc[ai][bj][m][n], 0, 0, 0); __builtin_amdgcn_s_setprio(0); } while (0)
; #define PG8_WAIT_V(n) asm volatile("s_waitcnt vmcnt(" #n ")" ::: "memory")
; #define PG8_WAIT_L(n) asm volatile("s_waitcnt lgkmcnt(" #n ")" ::: "memory")
; #define PG8_BAR __builtin_amdgcn_s_barrier()
; #define PG8_SCHED __builtin_amdgcn_sched_barrier(0)
; template <class Epi, class Sched, bool ALIGN_EPI = false, bool SP2 = false>
; __device__ __forceinline__ void gemm_phase(PG8_LAS unsigned char* lds, const Gemm g, const Sched& S, const Epi& E, const int wave_id) {
;     ...
;             PG8_LDB(B0, 1, 0); PG8_LDB(B1, 1, 1); PG8_SCHED; PG8_LDA(At, 1, 0); PG8_STAGE(PG8_SA(0, 1), a2 + hstep, voffA);
;             PG8_WAIT_V(8); PG8_WAIT_L(0); PG8_BAR; PG8_MMA(0, 0, At, B0); PG8_MMA(0, 1, At, B1); PG8_BAR; PG8_SCHED;
;             PG8_LDA(At, 1, 1); PG8_STAGE(PG8_SB(1, 0), b3, voffB); PG8_STAGE(PG8_SB(1, 1), b3 + hstep, voffB); PG8_STAGE(PG8_SA(1, 0), a3, voffA);
;             PG8_WAIT_V(8); PG8_WAIT_L(0); PG8_BAR; PG8_MMA(1, 0, At, B0); PG8_MMA(1, 1, At, B1); PG8_BAR; PG8_SCHED;
;     ...
;         if constexpr (ALIGN_EPI) { if (wr == 0) PG8_BAR; }
	s_add_i32 s77, 0, 0x18000
	s_add_i32 s79, 0, 0x1c000
	s_add_u32 s18, s42, 0x160000
	s_addc_u32 s19, s43, 0
	s_mov_b32 m0, s56
	s_nop 0
	global_load_lds_dwordx4 v190, s[18:19]
	ds_read_b128 v[118:121], v226 offset:32768
	ds_read_b128 v[122:125], v226 offset:33792
	ds_read_b128 v[130:133], v226 offset:34816
	ds_read_b128 v[134:137], v226 offset:35840
	ds_read_b128 v[146:149], v226 offset:49152
	ds_read_b128 v[150:153], v226 offset:50176
	ds_read_b128 v[154:157], v226 offset:51200
	ds_read_b128 v[158:161], v226 offset:52224
	s_mov_b32 m0, s57
	s_nop 0
	global_load_lds_dwordx4 v206, s[18:19]
	ds_read_b128 v[162:165], v222 offset:32768
	ds_read_b128 v[166:169], v222 offset:33792
	ds_read_b128 v[170:173], v222 offset:34816
	ds_read_b128 v[174:177], v222 offset:35840
	ds_read_b128 v[178:181], v222 offset:36864
	ds_read_b128 v[182:185], v222 offset:37888
	ds_read_b128 v[186:189], v222 offset:38912
	ds_read_b128 v[214:217], v222 offset:39936
	s_waitcnt vmcnt(8)
	s_waitcnt lgkmcnt(0)
	s_barrier
	s_setprio 1
	s_waitcnt lgkmcnt(0)
	v_mfma_f32_16x16x32_bf16 v[142:145], v[118:121], v[162:165], v[142:145]
	v_mfma_f32_16x16x32_bf16 v[138:141], v[130:133], v[162:165], v[138:141]
	v_mfma_f32_16x16x32_bf16 v[106:109], v[130:133], v[170:173], v[106:109]
	v_mfma_f32_16x16x32_bf16 v[110:113], v[118:121], v[170:173], v[110:113]
	v_mfma_f32_16x16x32_bf16 v[94:97], v[118:121], v[178:181], v[94:97]
	v_mfma_f32_16x16x32_bf16 v[90:93], v[130:133], v[178:181], v[90:93]
	v_mfma_f32_16x16x32_bf16 v[74:77], v[130:133], v[186:189], v[74:77]
	v_mfma_f32_16x16x32_bf16 v[78:81], v[118:121], v[186:189], v[78:81]
	v_mfma_f32_16x16x32_bf16 v[142:145], v[122:125], v[166:169], v[142:145]
	v_mfma_f32_16x16x32_bf16 v[138:141], v[134:137], v[166:169], v[138:141]
	v_mfma_f32_16x16x32_bf16 v[106:109], v[134:137], v[174:177], v[106:109]
	v_mfma_f32_16x16x32_bf16 v[110:113], v[122:125], v[174:177], v[110:113]
	v_mfma_f32_16x16x32_bf16 v[94:97], v[122:125], v[182:185], v[94:97]
	v_mfma_f32_16x16x32_bf16 v[90:93], v[134:137], v[182:185], v[90:93]
	v_mfma_f32_16x16x32_bf16 v[74:77], v[134:137], v[214:217], v[74:77]
	v_mfma_f32_16x16x32_bf16 v[78:81], v[122:125], v[214:217], v[78:81]
	s_setprio 0
	s_setprio 1
	v_mfma_f32_16x16x32_bf16 v[126:129], v[146:149], v[162:165], v[126:129]
	v_mfma_f32_16x16x32_bf16 v[114:117], v[154:157], v[162:165], v[114:117]
	v_mfma_f32_16x16x32_bf16 v[98:101], v[154:157], v[170:173], v[98:101]
	v_mfma_f32_16x16x32_bf16 v[102:105], v[146:149], v[170:173], v[102:105]
	v_mfma_f32_16x16x32_bf16 v[86:89], v[146:149], v[178:181], v[86:89]
	v_mfma_f32_16x16x32_bf16 v[82:85], v[154:157], v[178:181], v[82:85]
	v_mfma_f32_16x16x32_bf16 v[66:69], v[154:157], v[186:189], v[66:69]
	v_mfma_f32_16x16x32_bf16 v[70:73], v[146:149], v[186:189], v[70:73]
	v_mfma_f32_16x16x32_bf16 v[126:129], v[150:153], v[166:169], v[126:129]
	v_mfma_f32_16x16x32_bf16 v[114:117], v[158:161], v[166:169], v[114:117]
	v_mfma_f32_16x16x32_bf16 v[98:101], v[158:161], v[174:177], v[98:101]
	v_mfma_f32_16x16x32_bf16 v[102:105], v[150:153], v[174:177], v[102:105]
	v_mfma_f32_16x16x32_bf16 v[86:89], v[150:153], v[182:185], v[86:89]
	v_mfma_f32_16x16x32_bf16 v[82:85], v[158:161], v[182:185], v[82:85]
	v_mfma_f32_16x16x32_bf16 v[66:69], v[158:161], v[214:217], v[66:69]
	v_mfma_f32_16x16x32_bf16 v[70:73], v[150:153], v[214:217], v[70:73]
	s_setprio 0
	s_barrier
	s_add_u32 vcc_lo, s42, 0x80
	s_addc_u32 vcc_hi, s43, 0
	s_mov_b32 m0, s68
	s_nop 0
	global_load_lds_dwordx4 v190, vcc
	ds_read_b128 v[162:165], v222 offset:49152
	ds_read_b128 v[166:169], v222 offset:50176
	s_mov_b32 m0, s69
	s_add_i32 s18, s77, s49
	global_load_lds_dwordx4 v206, vcc
	ds_read_b128 v[170:173], v222 offset:51200
	ds_read_b128 v[174:177], v222 offset:52224
	s_add_u32 vcc_lo, s40, 0x80
	s_addc_u32 vcc_hi, s41, 0
	s_mov_b32 m0, s18
	s_nop 0
	global_load_lds_dwordx4 v192, vcc
	ds_read_b128 v[178:181], v222 offset:53248
	ds_read_b128 v[182:185], v222 offset:54272
	s_add_i32 m0, s18, 0x2000
	s_add_u32 s18, s40, 0x160080
	s_addc_u32 s19, s41, 0
	global_load_lds_dwordx4 v208, vcc
	ds_read_b128 v[186:189], v222 offset:55296
	ds_read_b128 v[214:217], v222 offset:56320
	s_add_i32 s40, s79, s49
	s_mov_b32 m0, s40
	s_nop 0
	global_load_lds_dwordx4 v192, s[18:19]
	s_add_i32 m0, s40, 0x2000
	s_nop 0
	global_load_lds_dwordx4 v208, s[18:19]
	s_waitcnt vmcnt(8)
	s_waitcnt lgkmcnt(0)
	s_barrier
	s_setprio 1
	s_waitcnt lgkmcnt(0)
	v_mfma_f32_16x16x32_bf16 v[62:65], v[118:121], v[162:165], v[62:65]
	v_mfma_f32_16x16x32_bf16 v[58:61], v[130:133], v[162:165], v[58:61]
	v_mfma_f32_16x16x32_bf16 v[42:45], v[130:133], v[170:173], v[42:45]
	v_mfma_f32_16x16x32_bf16 v[46:49], v[118:121], v[170:173], v[46:49]
	v_mfma_f32_16x16x32_bf16 v[30:33], v[118:121], v[178:181], v[30:33]
	v_mfma_f32_16x16x32_bf16 v[26:29], v[130:133], v[178:181], v[26:29]
	v_mfma_f32_16x16x32_bf16 v[10:13], v[130:133], v[186:189], v[10:13]
	v_mfma_f32_16x16x32_bf16 v[14:17], v[118:121], v[186:189], v[14:17]
	v_mfma_f32_16x16x32_bf16 v[62:65], v[122:125], v[166:169], v[62:65]
	v_mfma_f32_16x16x32_bf16 v[58:61], v[134:137], v[166:169], v[58:61]
	v_mfma_f32_16x16x32_bf16 v[42:45], v[134:137], v[174:177], v[42:45]
	v_mfma_f32_16x16x32_bf16 v[46:49], v[122:125], v[174:177], v[46:49]
	v_mfma_f32_16x16x32_bf16 v[30:33], v[122:125], v[182:185], v[30:33]
	v_mfma_f32_16x16x32_bf16 v[26:29], v[134:137], v[182:185], v[26:29]
	v_mfma_f32_16x16x32_bf16 v[10:13], v[134:137], v[214:217], v[10:13]
	v_mfma_f32_16x16x32_bf16 v[14:17], v[122:125], v[214:217], v[14:17]
	s_setprio 0
	s_setprio 1
	v_mfma_f32_16x16x32_bf16 v[54:57], v[146:149], v[162:165], v[54:57]
	v_mfma_f32_16x16x32_bf16 v[50:53], v[154:157], v[162:165], v[50:53]
	v_mfma_f32_16x16x32_bf16 v[34:37], v[154:157], v[170:173], v[34:37]
	v_mfma_f32_16x16x32_bf16 v[38:41], v[146:149], v[170:173], v[38:41]
	v_mfma_f32_16x16x32_bf16 v[22:25], v[146:149], v[178:181], v[22:25]
	v_mfma_f32_16x16x32_bf16 v[18:21], v[154:157], v[178:181], v[18:21]
	v_mfma_f32_16x16x32_bf16 v[2:5], v[154:157], v[186:189], v[2:5]
	v_mfma_f32_16x16x32_bf16 v[6:9], v[146:149], v[186:189], v[6:9]
	v_mfma_f32_16x16x32_bf16 v[54:57], v[150:153], v[166:169], v[54:57]
	v_mfma_f32_16x16x32_bf16 v[50:53], v[158:161], v[166:169], v[50:53]
	v_mfma_f32_16x16x32_bf16 v[34:37], v[158:161], v[174:177], v[34:37]
	v_mfma_f32_16x16x32_bf16 v[38:41], v[150:153], v[174:177], v[38:41]
	v_mfma_f32_16x16x32_bf16 v[22:25], v[150:153], v[182:185], v[22:25]
	v_mfma_f32_16x16x32_bf16 v[18:21], v[158:161], v[182:185], v[18:21]
	v_mfma_f32_16x16x32_bf16 v[2:5], v[158:161], v[214:217], v[2:5]
	v_mfma_f32_16x16x32_bf16 v[6:9], v[150:153], v[214:217], v[6:9]
	s_setprio 0
	s_barrier
	s_add_i32 s76, s76, 2
	s_add_u32 s74, s74, 0x100
	s_addc_u32 s75, s75, 0
	s_cmpk_gt_u32 s76, 0x55
	s_mov_b64 s[18:19], s[20:21]
	s_cbranch_scc0 .LBB0_759
	s_and_b64 vcc, exec, s[10:11]
	s_cbranch_vccz .LBB0_762
	s_barrier

; #define PG8_STAGE(bufoff, gbase, voff) do { _Pragma("unroll") for (int _i = 0; _i < 2; ++_i) \
;         __builtin_amdgcn_global_load_lds((const unsigned*)((const char*)(gbase) + (voff)[_i]), (PG8_LAS unsigned*)(lds + (bufoff) + ldsw + _i * 8192), 16, 0, 0); } while (0)
; #define PG8_LDA(dst, b, h) do { _Pragma("unroll") for (int m = 0; m < 4; ++m) _Pragma("unroll") for (int k = 0; k < 2; ++k) dst[m][k] = *(const PG8_LAS bf16x8*)(lds + PG8_SA(b, h) + aoff + m * 2048 + k * 1024); } while (0)
; #define PG8_LDB(dst, b, h) do { _Pragma("unroll") for (int n = 0; n < 2; ++n) _Pragma("unroll") for (int k = 0; k < 2; ++k) dst[n][k] = *(const PG8_LAS bf16x8*)(lds + PG8_SB(b, h) + boff + n * 2048 + k * 1024); } while (0)
; #define PG8_MMA(ai, bj, At, Bt) do { __builtin_amdgcn_s_setprio(1); _Pragma("unroll") for (int m = 0; m < 4; ++m) _Pragma("unroll") for (int n = 0; n < 2; ++n) _Pragma("unroll") for (int k = 0; k < 2; ++k) \
;         acc[ai][bj][m][n] = __builtin_amdgcn_mfma_f32_16x16x32_bf16(Bt[n][k], At[m][k], acc[ai][bj][m][n], 0, 0, 0); __builtin_amdgcn_s_setprio(0); } while (0)
; #define PG8_WAIT_V(n) asm volatile("s_waitcnt vmcnt(" #n ")" ::: "memory")
; #define PG8_WAIT_L(n) asm volatile("s_waitcnt lgkmcnt(" #n ")" ::: "memory")
; #define PG8_BAR __builtin_amdgcn_s_barrier()
; template <class Epi, class Sched, bool ALIGN_EPI = false, bool SP2 = false>
; __device__ __forceinline__ void gemm_phase(PG8_LAS unsigned char* lds, const Gemm g, const Sched& S, const Epi& E, const int wave_id) {
;     ...
;             const char* a1 = cA + (size_t)(t + 1) * kstep;
;             const char* a2 = last ? nA : cA + (size_t)(t + 2) * kstep; const char* b2 = last ? nB : cB + (size_t)(t + 2) * kstep;
;             const char* a3 = a2 + kstep; const char* b3 = b2 + kstep;
;             if (last && has_next) S.a_ready(nxt);
;             if constexpr (SP2) {
;             PG8_LDB(B0, 0, 0); PG8_LDB(B1, 0, 1); PG8_SCHED; PG8_LDA(At, 0, 0); PG8_STAGE(PG8_SA(1, 1), a1 + hstep, voffA);
;             PG8_WAIT_V(8); PG8_WAIT_L(0); PG8_BAR; PG8_MMA(0, 0, At, B0); PG8_MMA(0, 1, At, B1); PG8_BAR; PG8_SCHED;
;             PG8_LDA(At, 0, 1); PG8_STAGE(PG8_SB(0, 0), b2, voffB); PG8_STAGE(PG8_SB(0, 1), b2 + hstep, voffB); PG8_STAGE(PG8_SA(0, 0), a2, voffA);
;             PG8_WAIT_V(8); PG8_WAIT_L(0); PG8_BAR; PG8_MMA(1, 0, At, B0); PG8_MMA(1, 1, At, B1); PG8_BAR; PG8_SCHED;
.LBB0_799:
	s_add_u32 s52, s14, s44
	s_addc_u32 s53, s15, s45
	s_add_u32 s48, s52, 0x100
	s_addc_u32 s49, s53, 0
	s_and_b64 s[46:47], s[42:43], exec
	s_cselect_b32 s47, s19, s49
	s_cselect_b32 s46, s77, s48
	s_add_u32 s44, s12, s44
	s_addc_u32 s45, s13, s45
	s_add_u32 s44, s44, 0x100
	s_addc_u32 s45, s45, 0
	s_add_i32 s96, 0, 0x10000
	s_and_b64 s[42:43], s[42:43], exec
	s_cselect_b32 s49, s17, s45
	s_cselect_b32 s48, s79, s44
	s_add_i32 s43, 0, 0x14000
	s_add_u32 s82, s52, 0x10080
	s_addc_u32 s83, s53, 0
	s_add_i32 s93, s96, s68
	s_add_i32 m0, s69, 0xc000
	s_add_i32 vcc_lo, s69, 0xe000
	s_add_i32 s88, s93, 0x2000
	v_add_u32_e32 v141, s96, v138
	s_add_u32 s52, s48, 0x10000
	ds_read_b128 v[142:145], v141
	ds_read_b128 v[146:149], v141 offset:1024
	ds_read_b128 v[150:153], v141 offset:2048
	ds_read_b128 v[154:157], v141 offset:3072
	v_add_u32_e32 v141, s43, v138
	s_addc_u32 s53, s49, 0
	s_add_i32 s92, s43, s68
	ds_read_b128 v[158:161], v141
	ds_read_b128 v[162:165], v141 offset:1024
	ds_read_b128 v[166:169], v141 offset:2048
	ds_read_b128 v[170:173], v141 offset:3072
	s_add_i32 s89, s92, 0x2000
	s_add_i32 s85, 0, 0x18000
	s_add_i32 s84, 0, 0x1c000
	s_add_u32 s44, s46, 0x10000
	s_addc_u32 s45, s47, 0
	s_add_i32 s81, s85, s68
	s_add_i32 s80, s81, 0x2000
	s_add_u32 s42, s48, 0x10080
	s_addc_u32 s43, s49, 0
	s_add_i32 s97, s84, s68
	s_add_i32 s96, s97, 0x2000
	v_lshl_add_u64 v[226:227], s[82:83], 0, v[130:131]
	ds_read_b128 v[174:177], v140
	ds_read_b128 v[178:181], v140 offset:1024
	ds_read_b128 v[182:185], v140 offset:2048
	ds_read_b128 v[186:189], v140 offset:3072
	ds_read_b128 v[190:193], v140 offset:4096
	ds_read_b128 v[206:209], v140 offset:5120
	ds_read_b128 v[210:213], v140 offset:6144
	ds_read_b128 v[214:217], v140 offset:7168
	global_load_lds_dwordx4 v[226:227], off
	v_lshl_add_u64 v[226:227], s[82:83], 0, v[134:135]
	s_mov_b32 m0, vcc_lo
	s_nop 0
	global_load_lds_dwordx4 v[226:227], off
	s_waitcnt vmcnt(8)
	s_waitcnt lgkmcnt(0)
	s_barrier
	s_setprio 1
	s_waitcnt lgkmcnt(0)
	v_mfma_f32_16x16x32_bf16 v[126:129], v[142:145], v[174:177], v[126:129]
	v_mfma_f32_16x16x32_bf16 v[122:125], v[150:153], v[174:177], v[122:125]
	v_mfma_f32_16x16x32_bf16 v[114:117], v[150:153], v[182:185], v[114:117]
	v_mfma_f32_16x16x32_bf16 v[118:121], v[142:145], v[182:185], v[118:121]
	v_mfma_f32_16x16x32_bf16 v[102:105], v[142:145], v[190:193], v[102:105]
	v_mfma_f32_16x16x32_bf16 v[98:101], v[150:153], v[190:193], v[98:101]
	v_mfma_f32_16x16x32_bf16 v[82:85], v[150:153], v[210:213], v[82:85]
	v_mfma_f32_16x16x32_bf16 v[86:89], v[142:145], v[210:213], v[86:89]
	v_mfma_f32_16x16x32_bf16 v[126:129], v[146:149], v[178:181], v[126:129]
	v_mfma_f32_16x16x32_bf16 v[122:125], v[154:157], v[178:181], v[122:125]
	v_mfma_f32_16x16x32_bf16 v[114:117], v[154:157], v[186:189], v[114:117]
	v_mfma_f32_16x16x32_bf16 v[118:121], v[146:149], v[186:189], v[118:121]
	v_mfma_f32_16x16x32_bf16 v[102:105], v[146:149], v[206:209], v[102:105]
	v_mfma_f32_16x16x32_bf16 v[98:101], v[154:157], v[206:209], v[98:101]
	v_mfma_f32_16x16x32_bf16 v[82:85], v[154:157], v[214:217], v[82:85]
	v_mfma_f32_16x16x32_bf16 v[86:89], v[146:149], v[214:217], v[86:89]
	s_setprio 0
	s_setprio 1
	v_mfma_f32_16x16x32_bf16 v[110:113], v[158:161], v[174:177], v[110:113]
	v_mfma_f32_16x16x32_bf16 v[106:109], v[166:169], v[174:177], v[106:109]
	v_mfma_f32_16x16x32_bf16 v[90:93], v[166:169], v[182:185], v[90:93]
	v_mfma_f32_16x16x32_bf16 v[94:97], v[158:161], v[182:185], v[94:97]
	v_mfma_f32_16x16x32_bf16 v[78:81], v[158:161], v[190:193], v[78:81]
	v_mfma_f32_16x16x32_bf16 v[74:77], v[166:169], v[190:193], v[74:77]
	v_mfma_f32_16x16x32_bf16 v[66:69], v[166:169], v[210:213], v[66:69]
	v_mfma_f32_16x16x32_bf16 v[70:73], v[158:161], v[210:213], v[70:73]
	v_mfma_f32_16x16x32_bf16 v[110:113], v[162:165], v[178:181], v[110:113]
	v_mfma_f32_16x16x32_bf16 v[106:109], v[170:173], v[178:181], v[106:109]
	v_mfma_f32_16x16x32_bf16 v[90:93], v[170:173], v[186:189], v[90:93]
	v_mfma_f32_16x16x32_bf16 v[94:97], v[162:165], v[186:189], v[94:97]
	v_mfma_f32_16x16x32_bf16 v[78:81], v[162:165], v[206:209], v[78:81]
	v_mfma_f32_16x16x32_bf16 v[74:77], v[170:173], v[206:209], v[74:77]
	v_mfma_f32_16x16x32_bf16 v[66:69], v[170:173], v[214:217], v[66:69]
	v_mfma_f32_16x16x32_bf16 v[70:73], v[162:165], v[214:217], v[70:73]
	s_setprio 0
	s_barrier
	s_mov_b32 m0, s93
	v_lshl_add_u64 v[226:227], s[48:49], 0, v[132:133]
	ds_read_b128 v[174:177], v140 offset:16384
	ds_read_b128 v[178:181], v140 offset:17408
	ds_read_b128 v[182:185], v140 offset:18432
	ds_read_b128 v[186:189], v140 offset:19456
	ds_read_b128 v[190:193], v140 offset:20480
	ds_read_b128 v[206:209], v140 offset:21504
	ds_read_b128 v[210:213], v140 offset:22528
	ds_read_b128 v[214:217], v140 offset:23552
	global_load_lds_dwordx4 v[226:227], off
	v_lshl_add_u64 v[228:229], s[48:49], 0, v[136:137]
	s_mov_b32 m0, s88
	v_lshl_add_u64 v[230:231], s[52:53], 0, v[132:133]
	global_load_lds_dwordx4 v[228:229], off
	s_mov_b32 m0, s92
	v_lshl_add_u64 v[234:235], s[46:47], 0, v[134:135]
	global_load_lds_dwordx4 v[230:231], off
	v_lshl_add_u64 v[230:231], s[52:53], 0, v[136:137]
	s_mov_b32 m0, s89
	s_nop 0
	global_load_lds_dwordx4 v[230:231], off
	v_lshl_add_u64 v[230:231], s[46:47], 0, v[130:131]
	s_mov_b32 m0, s69
	s_nop 0
	global_load_lds_dwordx4 v[230:231], off
	s_mov_b32 m0, s70
	s_nop 0
	global_load_lds_dwordx4 v[234:235], off
	s_waitcnt vmcnt(8)
	s_waitcnt lgkmcnt(0)
	s_barrier
; #define PG8_STAGE(bufoff, gbase, voff) do { _Pragma("unroll") for (int _i = 0; _i < 2; ++_i) \
;         __builtin_amdgcn_global_load_lds((const unsigned*)((const char*)(gbase) + (voff)[_i]), (PG8_LAS unsigned*)(lds + (bufoff) + ldsw + _i * 8192), 16, 0, 0); } while (0)
; #define PG8_LDA(dst, b, h) do { _Pragma("unroll") for (int m = 0; m < 4; ++m) _Pragma("unroll") for (int k = 0; k < 2; ++k) dst[m][k] = *(const PG8_LAS bf16x8*)(lds + PG8_SA(b, h) + aoff + m * 2048 + k * 1024); } while (0)
; #define PG8_LDB(dst, b, h) do { _Pragma("unroll") for (int n = 0; n < 2; ++n) _Pragma("unroll") for (int k = 0; k < 2; ++k) dst[n][k] = *(const PG8_LAS bf16x8*)(lds + PG8_SB(b, h) + boff + n * 2048 + k * 1024); } while (0)
; #define PG8_MMA(ai, bj, At, Bt) do { __builtin_amdgcn_s_setprio(1); _Pragma("unroll") for (int m = 0; m < 4; ++m) _Pragma("unroll") for (int n = 0; n < 2; ++n) _Pragma("unroll") for (int k = 0; k < 2; ++k) \
;         acc[ai][bj][m][n] = __builtin_amdgcn_mfma_f32_16x16x32_bf16(Bt[n][k], At[m][k], acc[ai][bj][m][n], 0, 0, 0); __builtin_amdgcn_s_setprio(0); } while (0)
; #define PG8_WAIT_V(n) asm volatile("s_waitcnt vmcnt(" #n ")" ::: "memory")
; #define PG8_WAIT_L(n) asm volatile("s_waitcnt lgkmcnt(" #n ")" ::: "memory")
; #define PG8_BAR __builtin_amdgcn_s_barrier()
; #define PG8_SCHED __builtin_amdgcn_sched_barrier(0)
; template <class Epi, class Sched, bool ALIGN_EPI = false, bool SP2 = false>
; __device__ __forceinline__ void gemm_phase(PG8_LAS unsigned char* lds, const Gemm g, const Sched& S, const Epi& E, const int wave_id) {
;     ...
;             PG8_WAIT_V(8); PG8_WAIT_L(0); PG8_BAR; PG8_MMA(1, 0, At, B0); PG8_MMA(1, 1, At, B1); PG8_BAR; PG8_SCHED;
;             PG8_LDB(B0, 1, 0); PG8_LDB(B1, 1, 1); PG8_SCHED; PG8_LDA(At, 1, 0); PG8_STAGE(PG8_SA(0, 1), a2 + hstep, voffA);
;             PG8_WAIT_V(8); PG8_WAIT_L(0); PG8_BAR; PG8_MMA(0, 0, At, B0); PG8_MMA(0, 1, At, B1); PG8_BAR; PG8_SCHED;
;             PG8_LDA(At, 1, 1); PG8_STAGE(PG8_SB(1, 0), b3, voffB); PG8_STAGE(PG8_SB(1, 1), b3 + hstep, voffB); PG8_STAGE(PG8_SA(1, 0), a3, voffA);
	s_setprio 1
	s_waitcnt lgkmcnt(0)
	v_mfma_f32_16x16x32_bf16 v[62:65], v[142:145], v[174:177], v[62:65]
	v_mfma_f32_16x16x32_bf16 v[58:61], v[150:153], v[174:177], v[58:61]
	v_mfma_f32_16x16x32_bf16 v[50:53], v[150:153], v[182:185], v[50:53]
	v_mfma_f32_16x16x32_bf16 v[54:57], v[142:145], v[182:185], v[54:57]
	v_mfma_f32_16x16x32_bf16 v[38:41], v[142:145], v[190:193], v[38:41]
	v_mfma_f32_16x16x32_bf16 v[34:37], v[150:153], v[190:193], v[34:37]
	v_mfma_f32_16x16x32_bf16 v[18:21], v[150:153], v[210:213], v[18:21]
	v_mfma_f32_16x16x32_bf16 v[22:25], v[142:145], v[210:213], v[22:25]
	v_mfma_f32_16x16x32_bf16 v[62:65], v[146:149], v[178:181], v[62:65]
	v_mfma_f32_16x16x32_bf16 v[58:61], v[154:157], v[178:181], v[58:61]
	v_mfma_f32_16x16x32_bf16 v[50:53], v[154:157], v[186:189], v[50:53]
	v_mfma_f32_16x16x32_bf16 v[54:57], v[146:149], v[186:189], v[54:57]
	v_mfma_f32_16x16x32_bf16 v[38:41], v[146:149], v[206:209], v[38:41]
	v_mfma_f32_16x16x32_bf16 v[34:37], v[154:157], v[206:209], v[34:37]
	v_mfma_f32_16x16x32_bf16 v[18:21], v[154:157], v[214:217], v[18:21]
	v_mfma_f32_16x16x32_bf16 v[22:25], v[146:149], v[214:217], v[22:25]
	s_setprio 0
	s_setprio 1
	v_mfma_f32_16x16x32_bf16 v[46:49], v[158:161], v[174:177], v[46:49]
	v_mfma_f32_16x16x32_bf16 v[42:45], v[166:169], v[174:177], v[42:45]
	v_mfma_f32_16x16x32_bf16 v[26:29], v[166:169], v[182:185], v[26:29]
	v_mfma_f32_16x16x32_bf16 v[30:33], v[158:161], v[182:185], v[30:33]
	v_mfma_f32_16x16x32_bf16 v[14:17], v[158:161], v[190:193], v[14:17]
	v_mfma_f32_16x16x32_bf16 v[10:13], v[166:169], v[190:193], v[10:13]
	v_mfma_f32_16x16x32_bf16 v[2:5], v[166:169], v[210:213], v[2:5]
	v_mfma_f32_16x16x32_bf16 v[6:9], v[158:161], v[210:213], v[6:9]
	v_mfma_f32_16x16x32_bf16 v[46:49], v[162:165], v[178:181], v[46:49]
	v_mfma_f32_16x16x32_bf16 v[42:45], v[170:173], v[178:181], v[42:45]
	v_mfma_f32_16x16x32_bf16 v[26:29], v[170:173], v[186:189], v[26:29]
	v_mfma_f32_16x16x32_bf16 v[30:33], v[162:165], v[186:189], v[30:33]
	v_mfma_f32_16x16x32_bf16 v[14:17], v[162:165], v[206:209], v[14:17]
	v_mfma_f32_16x16x32_bf16 v[10:13], v[170:173], v[206:209], v[10:13]
	v_mfma_f32_16x16x32_bf16 v[2:5], v[170:173], v[214:217], v[2:5]
	v_mfma_f32_16x16x32_bf16 v[6:9], v[162:165], v[214:217], v[6:9]
	s_setprio 0
	s_barrier
	v_add_u32_e32 v141, s85, v138
	ds_read_b128 v[142:145], v141
	ds_read_b128 v[146:149], v141 offset:1024
	ds_read_b128 v[150:153], v141 offset:2048
	ds_read_b128 v[154:157], v141 offset:3072
	v_add_u32_e32 v141, s84, v138
	ds_read_b128 v[158:161], v141
	ds_read_b128 v[162:165], v141 offset:1024
	ds_read_b128 v[166:169], v141 offset:2048
	ds_read_b128 v[170:173], v141 offset:3072
	s_mov_b32 m0, s71
	v_lshl_add_u64 v[236:237], s[44:45], 0, v[130:131]
	ds_read_b128 v[174:177], v140 offset:32768
	ds_read_b128 v[178:181], v140 offset:33792
	ds_read_b128 v[182:185], v140 offset:34816
	ds_read_b128 v[186:189], v140 offset:35840
	ds_read_b128 v[190:193], v140 offset:36864
	ds_read_b128 v[206:209], v140 offset:37888
	ds_read_b128 v[210:213], v140 offset:38912
	ds_read_b128 v[214:217], v140 offset:39936
	global_load_lds_dwordx4 v[236:237], off
	v_lshl_add_u64 v[236:237], s[44:45], 0, v[134:135]
	s_mov_b32 m0, s72
	s_nop 0
	global_load_lds_dwordx4 v[236:237], off
	s_waitcnt vmcnt(8)
	s_waitcnt lgkmcnt(0)
	s_barrier
	s_setprio 1
	s_waitcnt lgkmcnt(0)
	v_mfma_f32_16x16x32_bf16 v[126:129], v[142:145], v[174:177], v[126:129]
	v_mfma_f32_16x16x32_bf16 v[122:125], v[150:153], v[174:177], v[122:125]
	v_mfma_f32_16x16x32_bf16 v[114:117], v[150:153], v[182:185], v[114:117]
	v_mfma_f32_16x16x32_bf16 v[118:121], v[142:145], v[182:185], v[118:121]
	v_mfma_f32_16x16x32_bf16 v[102:105], v[142:145], v[190:193], v[102:105]
	v_mfma_f32_16x16x32_bf16 v[98:101], v[150:153], v[190:193], v[98:101]
	v_mfma_f32_16x16x32_bf16 v[82:85], v[150:153], v[210:213], v[82:85]
	v_mfma_f32_16x16x32_bf16 v[86:89], v[142:145], v[210:213], v[86:89]
	v_mfma_f32_16x16x32_bf16 v[126:129], v[146:149], v[178:181], v[126:129]
	v_mfma_f32_16x16x32_bf16 v[122:125], v[154:157], v[178:181], v[122:125]
	v_mfma_f32_16x16x32_bf16 v[114:117], v[154:157], v[186:189], v[114:117]
	v_mfma_f32_16x16x32_bf16 v[118:121], v[146:149], v[186:189], v[118:121]
	v_mfma_f32_16x16x32_bf16 v[102:105], v[146:149], v[206:209], v[102:105]
	v_mfma_f32_16x16x32_bf16 v[98:101], v[154:157], v[206:209], v[98:101]
	v_mfma_f32_16x16x32_bf16 v[82:85], v[154:157], v[214:217], v[82:85]
	v_mfma_f32_16x16x32_bf16 v[86:89], v[146:149], v[214:217], v[86:89]
	s_setprio 0
	s_setprio 1
	v_mfma_f32_16x16x32_bf16 v[110:113], v[158:161], v[174:177], v[110:113]
	v_mfma_f32_16x16x32_bf16 v[106:109], v[166:169], v[174:177], v[106:109]
	v_mfma_f32_16x16x32_bf16 v[90:93], v[166:169], v[182:185], v[90:93]
	v_mfma_f32_16x16x32_bf16 v[94:97], v[158:161], v[182:185], v[94:97]
	v_mfma_f32_16x16x32_bf16 v[78:81], v[158:161], v[190:193], v[78:81]
	v_mfma_f32_16x16x32_bf16 v[74:77], v[166:169], v[190:193], v[74:77]
	v_mfma_f32_16x16x32_bf16 v[66:69], v[166:169], v[210:213], v[66:69]
	v_mfma_f32_16x16x32_bf16 v[70:73], v[158:161], v[210:213], v[70:73]
	v_mfma_f32_16x16x32_bf16 v[110:113], v[162:165], v[178:181], v[110:113]
	v_mfma_f32_16x16x32_bf16 v[106:109], v[170:173], v[178:181], v[106:109]
	v_mfma_f32_16x16x32_bf16 v[90:93], v[170:173], v[186:189], v[90:93]
	v_mfma_f32_16x16x32_bf16 v[94:97], v[162:165], v[186:189], v[94:97]
	v_mfma_f32_16x16x32_bf16 v[78:81], v[162:165], v[206:209], v[78:81]
	v_mfma_f32_16x16x32_bf16 v[74:77], v[170:173], v[206:209], v[74:77]
	v_mfma_f32_16x16x32_bf16 v[66:69], v[170:173], v[214:217], v[66:69]
	v_mfma_f32_16x16x32_bf16 v[70:73], v[162:165], v[214:217], v[70:73]
	s_setprio 0
	s_barrier
; #define PG8_STAGE(bufoff, gbase, voff) do { _Pragma("unroll") for (int _i = 0; _i < 2; ++_i) \
;         __builtin_amdgcn_global_load_lds((const unsigned*)((const char*)(gbase) + (voff)[_i]), (PG8_LAS unsigned*)(lds + (bufoff) + ldsw + _i * 8192), 16, 0, 0); } while (0)
; #define PG8_LDA(dst, b, h) do { _Pragma("unroll") for (int m = 0; m < 4; ++m) _Pragma("unroll") for (int k = 0; k < 2; ++k) dst[m][k] = *(const PG8_LAS bf16x8*)(lds + PG8_SA(b, h) + aoff + m * 2048 + k * 1024); } while (0)
; #define PG8_MMA(ai, bj, At, Bt) do { __builtin_amdgcn_s_setprio(1); _Pragma("unroll") for (int m = 0; m < 4; ++m) _Pragma("unroll") for (int n = 0; n < 2; ++n) _Pragma("unroll") for (int k = 0; k < 2; ++k) \
;         acc[ai][bj][m][n] = __builtin_amdgcn_mfma_f32_16x16x32_bf16(Bt[n][k], At[m][k], acc[ai][bj][m][n], 0, 0, 0); __builtin_amdgcn_s_setprio(0); } while (0)
; #define PG8_WAIT_V(n) asm volatile("s_waitcnt vmcnt(" #n ")" ::: "memory")
; #define PG8_WAIT_L(n) asm volatile("s_waitcnt lgkmcnt(" #n ")" ::: "memory")
; #define PG8_BAR __builtin_amdgcn_s_barrier()
; #define PG8_SCHED __builtin_amdgcn_sched_barrier(0)
; template <class Epi, class Sched, bool ALIGN_EPI = false, bool SP2 = false>
; __device__ __forceinline__ void gemm_phase(PG8_LAS unsigned char* lds, const Gemm g, const Sched& S, const Epi& E, const int wave_id) {
;     ...
;             PG8_LDA(At, 1, 1); PG8_STAGE(PG8_SB(1, 0), b3, voffB); PG8_STAGE(PG8_SB(1, 1), b3 + hstep, voffB); PG8_STAGE(PG8_SA(1, 0), a3, voffA);
;             PG8_WAIT_V(8); PG8_WAIT_L(0); PG8_BAR; PG8_MMA(1, 0, At, B0); PG8_MMA(1, 1, At, B1); PG8_BAR; PG8_SCHED;
	s_mov_b32 m0, s81
	v_lshl_add_u64 v[226:227], v[226:227], 0, s[30:31]
	ds_read_b128 v[174:177], v140 offset:49152
	ds_read_b128 v[178:181], v140 offset:50176
	ds_read_b128 v[182:185], v140 offset:51200
	ds_read_b128 v[186:189], v140 offset:52224
	ds_read_b128 v[190:193], v140 offset:53248
	ds_read_b128 v[206:209], v140 offset:54272
	ds_read_b128 v[210:213], v140 offset:55296
	ds_read_b128 v[214:217], v140 offset:56320
	global_load_lds_dwordx4 v[226:227], off
	v_lshl_add_u64 v[226:227], v[228:229], 0, s[30:31]
	s_mov_b32 m0, s80
	s_nop 0
	global_load_lds_dwordx4 v[226:227], off
	v_lshl_add_u64 v[226:227], s[42:43], 0, v[132:133]
	s_mov_b32 m0, s97
	s_nop 0
	global_load_lds_dwordx4 v[226:227], off
	v_lshl_add_u64 v[226:227], s[42:43], 0, v[136:137]
	s_mov_b32 m0, s96
	s_nop 0
	global_load_lds_dwordx4 v[226:227], off
	v_lshl_add_u64 v[226:227], v[230:231], 0, s[30:31]
	s_mov_b32 m0, s73
	s_nop 0
	global_load_lds_dwordx4 v[226:227], off
	v_lshl_add_u64 v[226:227], v[234:235], 0, s[30:31]
	s_mov_b32 m0, s74
	s_nop 0
	global_load_lds_dwordx4 v[226:227], off
	s_waitcnt vmcnt(8)
	s_waitcnt lgkmcnt(0)
	s_barrier
	s_setprio 1
	s_waitcnt lgkmcnt(0)
	v_mfma_f32_16x16x32_bf16 v[62:65], v[142:145], v[174:177], v[62:65]
	v_mfma_f32_16x16x32_bf16 v[58:61], v[150:153], v[174:177], v[58:61]
	v_mfma_f32_16x16x32_bf16 v[50:53], v[150:153], v[182:185], v[50:53]
	v_mfma_f32_16x16x32_bf16 v[54:57], v[142:145], v[182:185], v[54:57]
	v_mfma_f32_16x16x32_bf16 v[38:41], v[142:145], v[190:193], v[38:41]
	v_mfma_f32_16x16x32_bf16 v[34:37], v[150:153], v[190:193], v[34:37]
	v_mfma_f32_16x16x32_bf16 v[18:21], v[150:153], v[210:213], v[18:21]
	v_mfma_f32_16x16x32_bf16 v[22:25], v[142:145], v[210:213], v[22:25]
	v_mfma_f32_16x16x32_bf16 v[62:65], v[146:149], v[178:181], v[62:65]
	v_mfma_f32_16x16x32_bf16 v[58:61], v[154:157], v[178:181], v[58:61]
	v_mfma_f32_16x16x32_bf16 v[50:53], v[154:157], v[186:189], v[50:53]
	v_mfma_f32_16x16x32_bf16 v[54:57], v[146:149], v[186:189], v[54:57]
	v_mfma_f32_16x16x32_bf16 v[38:41], v[146:149], v[206:209], v[38:41]
	v_mfma_f32_16x16x32_bf16 v[34:37], v[154:157], v[206:209], v[34:37]
	v_mfma_f32_16x16x32_bf16 v[18:21], v[154:157], v[214:217], v[18:21]
	v_mfma_f32_16x16x32_bf16 v[22:25], v[146:149], v[214:217], v[22:25]
	s_setprio 0
	s_setprio 1
	v_mfma_f32_16x16x32_bf16 v[46:49], v[158:161], v[174:177], v[46:49]
	v_mfma_f32_16x16x32_bf16 v[42:45], v[166:169], v[174:177], v[42:45]
	v_mfma_f32_16x16x32_bf16 v[26:29], v[166:169], v[182:185], v[26:29]
	v_mfma_f32_16x16x32_bf16 v[30:33], v[158:161], v[182:185], v[30:33]
	v_mfma_f32_16x16x32_bf16 v[14:17], v[158:161], v[190:193], v[14:17]
	v_mfma_f32_16x16x32_bf16 v[10:13], v[166:169], v[190:193], v[10:13]
	v_mfma_f32_16x16x32_bf16 v[2:5], v[166:169], v[210:213], v[2:5]
	v_mfma_f32_16x16x32_bf16 v[6:9], v[158:161], v[210:213], v[6:9]
	v_mfma_f32_16x16x32_bf16 v[46:49], v[162:165], v[178:181], v[46:49]
	v_mfma_f32_16x16x32_bf16 v[42:45], v[170:173], v[178:181], v[42:45]
	v_mfma_f32_16x16x32_bf16 v[26:29], v[170:173], v[186:189], v[26:29]
	v_mfma_f32_16x16x32_bf16 v[30:33], v[162:165], v[186:189], v[30:33]
	v_mfma_f32_16x16x32_bf16 v[14:17], v[162:165], v[206:209], v[14:17]
	v_mfma_f32_16x16x32_bf16 v[10:13], v[170:173], v[206:209], v[10:13]
	v_mfma_f32_16x16x32_bf16 v[2:5], v[170:173], v[214:217], v[2:5]
	v_mfma_f32_16x16x32_bf16 v[6:9], v[162:165], v[214:217], v[6:9]
	s_setprio 0
	s_barrier
	s_andn2_b64 vcc, exec, s[40:41]
	s_mov_b64 s[42:43], -1
	s_mov_b64 s[40:41], 0
	s_mov_b64 s[44:45], 0x100
	s_cbranch_vccz .LBB0_799
	s_and_b64 vcc, exec, s[10:11]
	s_cbranch_vccz .LBB0_802
	s_barrier

; #define PG8_STAGE(bufoff, gbase, voff) do { _Pragma("unroll") for (int _i = 0; _i < 2; ++_i) \
;         __builtin_amdgcn_global_load_lds((const unsigned*)((const char*)(gbase) + (voff)[_i]), (PG8_LAS unsigned*)(lds + (bufoff) + ldsw + _i * 8192), 16, 0, 0); } while (0)
; #define PG8_LDA(dst, b, h) do { _Pragma("unroll") for (int m = 0; m < 4; ++m) _Pragma("unroll") for (int k = 0; k < 2; ++k) dst[m][k] = *(const PG8_LAS bf16x8*)(lds + PG8_SA(b, h) + aoff + m * 2048 + k * 1024); } while (0)
; #define PG8_LDB(dst, b, h) do { _Pragma("unroll") for (int n = 0; n < 2; ++n) _Pragma("unroll") for (int k = 0; k < 2; ++k) dst[n][k] = *(const PG8_LAS bf16x8*)(lds + PG8_SB(b, h) + boff + n * 2048 + k * 1024); } while (0)
; #define PG8_MMA(ai, bj, At, Bt) do { __builtin_amdgcn_s_setprio(1); _Pragma("unroll") for (int m = 0; m < 4; ++m) _Pragma("unroll") for (int n = 0; n < 2; ++n) _Pragma("unroll") for (int k = 0; k < 2; ++k) \
;         acc[ai][bj][m][n] = __builtin_amdgcn_mfma_f32_16x16x32_bf16(Bt[n][k], At[m][k], acc[ai][bj][m][n], 0, 0, 0); __builtin_amdgcn_s_setprio(0); } while (0)
; #define PG8_WAIT_V(n) asm volatile("s_waitcnt vmcnt(" #n ")" ::: "memory")
; #define PG8_WAIT_L(n) asm volatile("s_waitcnt lgkmcnt(" #n ")" ::: "memory")
; template <class Epi, class Sched, bool ALIGN_EPI = false, bool SP2 = false>
; __device__ __forceinline__ void gemm_phase(PG8_LAS unsigned char* lds, const Gemm g, const Sched& S, const Epi& E, const int wave_id) {
;     ...
;             const bool last = (t == nt - 2);
;             const char* a1 = cA + (size_t)(t + 1) * kstep;
;             const char* a2 = last ? nA : cA + (size_t)(t + 2) * kstep; const char* b2 = last ? nB : cB + (size_t)(t + 2) * kstep;
;             const char* a3 = a2 + kstep; const char* b3 = b2 + kstep;
;             if (last && has_next) S.a_ready(nxt);
;             if constexpr (SP2) {
;             PG8_LDB(B0, 0, 0); PG8_LDB(B1, 0, 1); PG8_SCHED; PG8_LDA(At, 0, 0); PG8_STAGE(PG8_SA(1, 1), a1 + hstep, voffA);
;             PG8_WAIT_V(8); PG8_WAIT_L(0); PG8_BAR; PG8_MMA(0, 0, At, B0); PG8_MMA(0, 1, At, B1); PG8_BAR; PG8_SCHED;
;             PG8_LDA(At, 0, 1); PG8_STAGE(PG8_SB(0, 0), b2, voffB); PG8_STAGE(PG8_SB(0, 1), b2 + hstep, voffB); PG8_STAGE(PG8_SA(0, 0), a2, voffA);
;             PG8_WAIT_V(8); PG8_WAIT_L(0); PG8_BAR; PG8_MMA(1, 0, At, B0); PG8_MMA(1, 1, At, B1); PG8_BAR; PG8_SCHED;
.LBB0_904:
	s_add_u32 s52, s46, 0xfff80080
	s_addc_u32 s53, s47, -1
	s_add_i32 s85, 0, 0x10000
	s_cmp_eq_u32 s84, 28
	s_cselect_b32 s83, s21, s53
	s_cselect_b32 s82, s49, s52
	s_cselect_b32 s53, s19, s81
	s_cselect_b32 s52, s79, s80
	s_add_i32 s92, 0, 0x14000
	s_add_i32 m0, s70, 0xc000
	s_nop 0
	global_load_lds_dwordx4 v214, s[46:47]
	ds_read_b128 v[114:117], v226
	ds_read_b128 v[118:121], v226 offset:1024
	ds_read_b128 v[130:133], v226 offset:2048
	ds_read_b128 v[134:137], v226 offset:3072
	ds_read_b128 v[138:141], v226 offset:16384
	ds_read_b128 v[142:145], v226 offset:17408
	ds_read_b128 v[146:149], v226 offset:18432
	ds_read_b128 v[150:153], v226 offset:19456
	s_add_i32 m0, s70, 0xe000
	s_nop 0
	global_load_lds_dwordx4 v216, s[46:47]
	ds_read_b128 v[162:165], v244
	ds_read_b128 v[166:169], v244 offset:1024
	ds_read_b128 v[170:173], v244 offset:2048
	ds_read_b128 v[174:177], v244 offset:3072
	ds_read_b128 v[178:181], v244 offset:4096
	ds_read_b128 v[182:185], v244 offset:5120
	ds_read_b128 v[186:189], v244 offset:6144
	ds_read_b128 v[190:193], v244 offset:7168
	s_waitcnt vmcnt(8)
	s_waitcnt lgkmcnt(0)
	s_barrier
	s_setprio 1
	s_waitcnt lgkmcnt(0)
	v_mfma_f32_16x16x32_bf16 v[158:161], v[114:117], v[162:165], v[158:161]
	v_mfma_f32_16x16x32_bf16 v[154:157], v[130:133], v[162:165], v[154:157]
	v_mfma_f32_16x16x32_bf16 v[106:109], v[130:133], v[170:173], v[106:109]
	v_mfma_f32_16x16x32_bf16 v[110:113], v[114:117], v[170:173], v[110:113]
	v_mfma_f32_16x16x32_bf16 v[94:97], v[114:117], v[178:181], v[94:97]
	v_mfma_f32_16x16x32_bf16 v[90:93], v[130:133], v[178:181], v[90:93]
	v_mfma_f32_16x16x32_bf16 v[74:77], v[130:133], v[186:189], v[74:77]
	v_mfma_f32_16x16x32_bf16 v[78:81], v[114:117], v[186:189], v[78:81]
	v_mfma_f32_16x16x32_bf16 v[158:161], v[118:121], v[166:169], v[158:161]
	v_mfma_f32_16x16x32_bf16 v[154:157], v[134:137], v[166:169], v[154:157]
	v_mfma_f32_16x16x32_bf16 v[106:109], v[134:137], v[174:177], v[106:109]
	v_mfma_f32_16x16x32_bf16 v[110:113], v[118:121], v[174:177], v[110:113]
	v_mfma_f32_16x16x32_bf16 v[94:97], v[118:121], v[182:185], v[94:97]
	v_mfma_f32_16x16x32_bf16 v[90:93], v[134:137], v[182:185], v[90:93]
	v_mfma_f32_16x16x32_bf16 v[74:77], v[134:137], v[190:193], v[74:77]
	v_mfma_f32_16x16x32_bf16 v[78:81], v[118:121], v[190:193], v[78:81]
	s_setprio 0
	s_setprio 1
	v_mfma_f32_16x16x32_bf16 v[126:129], v[138:141], v[162:165], v[126:129]
	v_mfma_f32_16x16x32_bf16 v[122:125], v[146:149], v[162:165], v[122:125]
	v_mfma_f32_16x16x32_bf16 v[98:101], v[146:149], v[170:173], v[98:101]
	v_mfma_f32_16x16x32_bf16 v[102:105], v[138:141], v[170:173], v[102:105]
	v_mfma_f32_16x16x32_bf16 v[86:89], v[138:141], v[178:181], v[86:89]
	v_mfma_f32_16x16x32_bf16 v[82:85], v[146:149], v[178:181], v[82:85]
	v_mfma_f32_16x16x32_bf16 v[66:69], v[146:149], v[186:189], v[66:69]
	v_mfma_f32_16x16x32_bf16 v[70:73], v[138:141], v[186:189], v[70:73]
	v_mfma_f32_16x16x32_bf16 v[126:129], v[142:145], v[166:169], v[126:129]
	v_mfma_f32_16x16x32_bf16 v[122:125], v[150:153], v[166:169], v[122:125]
	v_mfma_f32_16x16x32_bf16 v[98:101], v[150:153], v[174:177], v[98:101]
	v_mfma_f32_16x16x32_bf16 v[102:105], v[142:145], v[174:177], v[102:105]
	v_mfma_f32_16x16x32_bf16 v[86:89], v[142:145], v[182:185], v[86:89]
	v_mfma_f32_16x16x32_bf16 v[82:85], v[150:153], v[182:185], v[82:85]
	v_mfma_f32_16x16x32_bf16 v[66:69], v[150:153], v[190:193], v[66:69]
	v_mfma_f32_16x16x32_bf16 v[70:73], v[142:145], v[190:193], v[70:73]
	s_setprio 0
	s_barrier
	s_add_i32 s85, s85, s69
	s_mov_b32 m0, s85
	s_nop 0
	global_load_lds_dwordx4 v208, s[52:53]
	ds_read_b128 v[162:165], v244 offset:16384
	ds_read_b128 v[166:169], v244 offset:17408
	s_add_i32 m0, s85, 0x2000
	s_add_u32 s88, s52, 0x80000
	s_addc_u32 s89, s53, 0
	s_add_i32 s85, s92, s69
	global_load_lds_dwordx4 v212, s[52:53]
	ds_read_b128 v[170:173], v244 offset:18432
	ds_read_b128 v[174:177], v244 offset:19456
	s_mov_b32 m0, s85
	s_nop 0
	global_load_lds_dwordx4 v208, s[88:89]
	ds_read_b128 v[178:181], v244 offset:20480
	ds_read_b128 v[182:185], v244 offset:21504
	s_add_i32 m0, s85, 0x2000
	s_nop 0
	global_load_lds_dwordx4 v212, s[88:89]
	ds_read_b128 v[186:189], v244 offset:22528
	ds_read_b128 v[190:193], v244 offset:23552
	s_mov_b32 m0, s70
	s_nop 0
	global_load_lds_dwordx4 v206, s[82:83]
	s_mov_b32 m0, s71
	s_nop 0
	global_load_lds_dwordx4 v210, s[82:83]
	s_waitcnt vmcnt(8)
	s_waitcnt lgkmcnt(0)
	s_barrier
	s_setprio 1
	s_waitcnt lgkmcnt(0)
	v_mfma_f32_16x16x32_bf16 v[62:65], v[114:117], v[162:165], v[62:65]
	v_mfma_f32_16x16x32_bf16 v[58:61], v[130:133], v[162:165], v[58:61]
	v_mfma_f32_16x16x32_bf16 v[42:45], v[130:133], v[170:173], v[42:45]
	v_mfma_f32_16x16x32_bf16 v[46:49], v[114:117], v[170:173], v[46:49]
	v_mfma_f32_16x16x32_bf16 v[30:33], v[114:117], v[178:181], v[30:33]
	v_mfma_f32_16x16x32_bf16 v[26:29], v[130:133], v[178:181], v[26:29]
	v_mfma_f32_16x16x32_bf16 v[10:13], v[130:133], v[186:189], v[10:13]
	v_mfma_f32_16x16x32_bf16 v[14:17], v[114:117], v[186:189], v[14:17]
	v_mfma_f32_16x16x32_bf16 v[62:65], v[118:121], v[166:169], v[62:65]
	v_mfma_f32_16x16x32_bf16 v[58:61], v[134:137], v[166:169], v[58:61]
	v_mfma_f32_16x16x32_bf16 v[42:45], v[134:137], v[174:177], v[42:45]
	v_mfma_f32_16x16x32_bf16 v[46:49], v[118:121], v[174:177], v[46:49]
	v_mfma_f32_16x16x32_bf16 v[30:33], v[118:121], v[182:185], v[30:33]
	v_mfma_f32_16x16x32_bf16 v[26:29], v[134:137], v[182:185], v[26:29]
	v_mfma_f32_16x16x32_bf16 v[10:13], v[134:137], v[190:193], v[10:13]
	v_mfma_f32_16x16x32_bf16 v[14:17], v[118:121], v[190:193], v[14:17]
	s_setprio 0
	s_setprio 1
	v_mfma_f32_16x16x32_bf16 v[54:57], v[138:141], v[162:165], v[54:57]
	v_mfma_f32_16x16x32_bf16 v[50:53], v[146:149], v[162:165], v[50:53]
	v_mfma_f32_16x16x32_bf16 v[34:37], v[146:149], v[170:173], v[34:37]
	v_mfma_f32_16x16x32_bf16 v[38:41], v[138:141], v[170:173], v[38:41]
	v_mfma_f32_16x16x32_bf16 v[22:25], v[138:141], v[178:181], v[22:25]
	v_mfma_f32_16x16x32_bf16 v[18:21], v[146:149], v[178:181], v[18:21]
	v_mfma_f32_16x16x32_bf16 v[2:5], v[146:149], v[186:189], v[2:5]
	v_mfma_f32_16x16x32_bf16 v[6:9], v[138:141], v[186:189], v[6:9]
	v_mfma_f32_16x16x32_bf16 v[54:57], v[142:145], v[166:169], v[54:57]
	v_mfma_f32_16x16x32_bf16 v[50:53], v[150:153], v[166:169], v[50:53]
	v_mfma_f32_16x16x32_bf16 v[34:37], v[150:153], v[174:177], v[34:37]
	v_mfma_f32_16x16x32_bf16 v[38:41], v[142:145], v[174:177], v[38:41]
	v_mfma_f32_16x16x32_bf16 v[22:25], v[142:145], v[182:185], v[22:25]
	v_mfma_f32_16x16x32_bf16 v[18:21], v[150:153], v[182:185], v[18:21]
	v_mfma_f32_16x16x32_bf16 v[2:5], v[150:153], v[190:193], v[2:5]
	v_mfma_f32_16x16x32_bf16 v[6:9], v[142:145], v[190:193], v[6:9]
	s_setprio 0
	s_barrier
; #define PG8_STAGE(bufoff, gbase, voff) do { _Pragma("unroll") for (int _i = 0; _i < 2; ++_i) \
;         __builtin_amdgcn_global_load_lds((const unsigned*)((const char*)(gbase) + (voff)[_i]), (PG8_LAS unsigned*)(lds + (bufoff) + ldsw + _i * 8192), 16, 0, 0); } while (0)
; #define PG8_LDA(dst, b, h) do { _Pragma("unroll") for (int m = 0; m < 4; ++m) _Pragma("unroll") for (int k = 0; k < 2; ++k) dst[m][k] = *(const PG8_LAS bf16x8*)(lds + PG8_SA(b, h) + aoff + m * 2048 + k * 1024); } while (0)
; #define PG8_LDB(dst, b, h) do { _Pragma("unroll") for (int n = 0; n < 2; ++n) _Pragma("unroll") for (int k = 0; k < 2; ++k) dst[n][k] = *(const PG8_LAS bf16x8*)(lds + PG8_SB(b, h) + boff + n * 2048 + k * 1024); } while (0)
; #define PG8_MMA(ai, bj, At, Bt) do { __builtin_amdgcn_s_setprio(1); _Pragma("unroll") for (int m = 0; m < 4; ++m) _Pragma("unroll") for (int n = 0; n < 2; ++n) _Pragma("unroll") for (int k = 0; k < 2; ++k) \
;         acc[ai][bj][m][n] = __builtin_amdgcn_mfma_f32_16x16x32_bf16(Bt[n][k], At[m][k], acc[ai][bj][m][n], 0, 0, 0); __builtin_amdgcn_s_setprio(0); } while (0)
; #define PG8_WAIT_V(n) asm volatile("s_waitcnt vmcnt(" #n ")" ::: "memory")
; #define PG8_WAIT_L(n) asm volatile("s_waitcnt lgkmcnt(" #n ")" ::: "memory")
; #define PG8_BAR __builtin_amdgcn_s_barrier()
; #define PG8_SCHED __builtin_amdgcn_sched_barrier(0)
; template <class Epi, class Sched, bool ALIGN_EPI = false, bool SP2 = false>
; __device__ __forceinline__ void gemm_phase(PG8_LAS unsigned char* lds, const Gemm g, const Sched& S, const Epi& E, const int wave_id) {
;     ...
;             PG8_LDB(B0, 1, 0); PG8_LDB(B1, 1, 1); PG8_SCHED; PG8_LDA(At, 1, 0); PG8_STAGE(PG8_SA(0, 1), a2 + hstep, voffA);
;             PG8_WAIT_V(8); PG8_WAIT_L(0); PG8_BAR; PG8_MMA(0, 0, At, B0); PG8_MMA(0, 1, At, B1); PG8_BAR; PG8_SCHED;
;             PG8_LDA(At, 1, 1); PG8_STAGE(PG8_SB(1, 0), b3, voffB); PG8_STAGE(PG8_SB(1, 1), b3 + hstep, voffB); PG8_STAGE(PG8_SA(1, 0), a3, voffA);
;             PG8_WAIT_V(8); PG8_WAIT_L(0); PG8_BAR; PG8_MMA(1, 0, At, B0); PG8_MMA(1, 1, At, B1); PG8_BAR; PG8_SCHED;
;     ...
;         if constexpr (ALIGN_EPI) { if (wr == 0) PG8_BAR; }
	s_add_i32 s85, 0, 0x18000
	s_add_i32 s88, 0, 0x1c000
	s_add_u32 s82, s82, 0x80000
	s_addc_u32 s83, s83, 0
	s_mov_b32 m0, s72
	s_nop 0
	global_load_lds_dwordx4 v206, s[82:83]
	ds_read_b128 v[114:117], v226 offset:32768
	ds_read_b128 v[118:121], v226 offset:33792
	ds_read_b128 v[130:133], v226 offset:34816
	ds_read_b128 v[134:137], v226 offset:35840
	ds_read_b128 v[138:141], v226 offset:49152
	ds_read_b128 v[142:145], v226 offset:50176
	ds_read_b128 v[146:149], v226 offset:51200
	ds_read_b128 v[150:153], v226 offset:52224
	s_mov_b32 m0, s73
	s_nop 0
	global_load_lds_dwordx4 v210, s[82:83]
	ds_read_b128 v[162:165], v244 offset:32768
	ds_read_b128 v[166:169], v244 offset:33792
	ds_read_b128 v[170:173], v244 offset:34816
	ds_read_b128 v[174:177], v244 offset:35840
	ds_read_b128 v[178:181], v244 offset:36864
	ds_read_b128 v[182:185], v244 offset:37888
	ds_read_b128 v[186:189], v244 offset:38912
	ds_read_b128 v[190:193], v244 offset:39936
	s_waitcnt vmcnt(8)
	s_waitcnt lgkmcnt(0)
	s_barrier
	s_setprio 1
	s_waitcnt lgkmcnt(0)
	v_mfma_f32_16x16x32_bf16 v[158:161], v[114:117], v[162:165], v[158:161]
	v_mfma_f32_16x16x32_bf16 v[154:157], v[130:133], v[162:165], v[154:157]
	v_mfma_f32_16x16x32_bf16 v[106:109], v[130:133], v[170:173], v[106:109]
	v_mfma_f32_16x16x32_bf16 v[110:113], v[114:117], v[170:173], v[110:113]
	v_mfma_f32_16x16x32_bf16 v[94:97], v[114:117], v[178:181], v[94:97]
	v_mfma_f32_16x16x32_bf16 v[90:93], v[130:133], v[178:181], v[90:93]
	v_mfma_f32_16x16x32_bf16 v[74:77], v[130:133], v[186:189], v[74:77]
	v_mfma_f32_16x16x32_bf16 v[78:81], v[114:117], v[186:189], v[78:81]
	v_mfma_f32_16x16x32_bf16 v[158:161], v[118:121], v[166:169], v[158:161]
	v_mfma_f32_16x16x32_bf16 v[154:157], v[134:137], v[166:169], v[154:157]
	v_mfma_f32_16x16x32_bf16 v[106:109], v[134:137], v[174:177], v[106:109]
	v_mfma_f32_16x16x32_bf16 v[110:113], v[118:121], v[174:177], v[110:113]
	v_mfma_f32_16x16x32_bf16 v[94:97], v[118:121], v[182:185], v[94:97]
	v_mfma_f32_16x16x32_bf16 v[90:93], v[134:137], v[182:185], v[90:93]
	v_mfma_f32_16x16x32_bf16 v[74:77], v[134:137], v[190:193], v[74:77]
	v_mfma_f32_16x16x32_bf16 v[78:81], v[118:121], v[190:193], v[78:81]
	s_setprio 0
	s_setprio 1
	v_mfma_f32_16x16x32_bf16 v[126:129], v[138:141], v[162:165], v[126:129]
	v_mfma_f32_16x16x32_bf16 v[122:125], v[146:149], v[162:165], v[122:125]
	v_mfma_f32_16x16x32_bf16 v[98:101], v[146:149], v[170:173], v[98:101]
	v_mfma_f32_16x16x32_bf16 v[102:105], v[138:141], v[170:173], v[102:105]
	v_mfma_f32_16x16x32_bf16 v[86:89], v[138:141], v[178:181], v[86:89]
	v_mfma_f32_16x16x32_bf16 v[82:85], v[146:149], v[178:181], v[82:85]
	v_mfma_f32_16x16x32_bf16 v[66:69], v[146:149], v[186:189], v[66:69]
	v_mfma_f32_16x16x32_bf16 v[70:73], v[138:141], v[186:189], v[70:73]
	v_mfma_f32_16x16x32_bf16 v[126:129], v[142:145], v[166:169], v[126:129]
	v_mfma_f32_16x16x32_bf16 v[122:125], v[150:153], v[166:169], v[122:125]
	v_mfma_f32_16x16x32_bf16 v[98:101], v[150:153], v[174:177], v[98:101]
	v_mfma_f32_16x16x32_bf16 v[102:105], v[142:145], v[174:177], v[102:105]
	v_mfma_f32_16x16x32_bf16 v[86:89], v[142:145], v[182:185], v[86:89]
	v_mfma_f32_16x16x32_bf16 v[82:85], v[150:153], v[182:185], v[82:85]
	v_mfma_f32_16x16x32_bf16 v[66:69], v[150:153], v[190:193], v[66:69]
	v_mfma_f32_16x16x32_bf16 v[70:73], v[142:145], v[190:193], v[70:73]
	s_setprio 0
	s_barrier
	s_add_u32 vcc_lo, s82, 0xfff80080
	s_addc_u32 vcc_hi, s83, -1
	s_mov_b32 m0, s76
	s_nop 0
	global_load_lds_dwordx4 v206, vcc
	ds_read_b128 v[162:165], v244 offset:49152
	ds_read_b128 v[166:169], v244 offset:50176
	s_mov_b32 m0, s77
	s_add_i32 s82, s85, s69
	global_load_lds_dwordx4 v210, vcc
	ds_read_b128 v[170:173], v244 offset:51200
	ds_read_b128 v[174:177], v244 offset:52224
	s_add_u32 vcc_lo, s52, 0x80
	s_addc_u32 vcc_hi, s53, 0
	s_mov_b32 m0, s82
	s_nop 0
	global_load_lds_dwordx4 v208, vcc
	ds_read_b128 v[178:181], v244 offset:53248
	ds_read_b128 v[182:185], v244 offset:54272
	s_add_i32 m0, s82, 0x2000
	s_add_u32 s52, s52, 0x80080
	s_addc_u32 s53, s53, 0
	global_load_lds_dwordx4 v212, vcc
	ds_read_b128 v[186:189], v244 offset:55296
	ds_read_b128 v[190:193], v244 offset:56320
	s_add_i32 s82, s88, s69
	s_mov_b32 m0, s82
	s_nop 0
	global_load_lds_dwordx4 v208, s[52:53]
	s_add_i32 m0, s82, 0x2000
	s_nop 0
	global_load_lds_dwordx4 v212, s[52:53]
	s_waitcnt vmcnt(8)
	s_waitcnt lgkmcnt(0)
	s_barrier
	s_setprio 1
	s_waitcnt lgkmcnt(0)
	v_mfma_f32_16x16x32_bf16 v[62:65], v[114:117], v[162:165], v[62:65]
	v_mfma_f32_16x16x32_bf16 v[58:61], v[130:133], v[162:165], v[58:61]
	v_mfma_f32_16x16x32_bf16 v[42:45], v[130:133], v[170:173], v[42:45]
	v_mfma_f32_16x16x32_bf16 v[46:49], v[114:117], v[170:173], v[46:49]
	v_mfma_f32_16x16x32_bf16 v[30:33], v[114:117], v[178:181], v[30:33]
	v_mfma_f32_16x16x32_bf16 v[26:29], v[130:133], v[178:181], v[26:29]
	v_mfma_f32_16x16x32_bf16 v[10:13], v[130:133], v[186:189], v[10:13]
	v_mfma_f32_16x16x32_bf16 v[14:17], v[114:117], v[186:189], v[14:17]
	v_mfma_f32_16x16x32_bf16 v[62:65], v[118:121], v[166:169], v[62:65]
	v_mfma_f32_16x16x32_bf16 v[58:61], v[134:137], v[166:169], v[58:61]
	v_mfma_f32_16x16x32_bf16 v[42:45], v[134:137], v[174:177], v[42:45]
	v_mfma_f32_16x16x32_bf16 v[46:49], v[118:121], v[174:177], v[46:49]
	v_mfma_f32_16x16x32_bf16 v[30:33], v[118:121], v[182:185], v[30:33]
	v_mfma_f32_16x16x32_bf16 v[26:29], v[134:137], v[182:185], v[26:29]
	v_mfma_f32_16x16x32_bf16 v[10:13], v[134:137], v[190:193], v[10:13]
	v_mfma_f32_16x16x32_bf16 v[14:17], v[118:121], v[190:193], v[14:17]
	s_setprio 0
	s_setprio 1
	v_mfma_f32_16x16x32_bf16 v[54:57], v[138:141], v[162:165], v[54:57]
	v_mfma_f32_16x16x32_bf16 v[50:53], v[146:149], v[162:165], v[50:53]
	v_mfma_f32_16x16x32_bf16 v[34:37], v[146:149], v[170:173], v[34:37]
	v_mfma_f32_16x16x32_bf16 v[38:41], v[138:141], v[170:173], v[38:41]
	v_mfma_f32_16x16x32_bf16 v[22:25], v[138:141], v[178:181], v[22:25]
	v_mfma_f32_16x16x32_bf16 v[18:21], v[146:149], v[178:181], v[18:21]
	v_mfma_f32_16x16x32_bf16 v[2:5], v[146:149], v[186:189], v[2:5]
	v_mfma_f32_16x16x32_bf16 v[6:9], v[138:141], v[186:189], v[6:9]
	v_mfma_f32_16x16x32_bf16 v[54:57], v[142:145], v[166:169], v[54:57]
	v_mfma_f32_16x16x32_bf16 v[50:53], v[150:153], v[166:169], v[50:53]
	v_mfma_f32_16x16x32_bf16 v[34:37], v[150:153], v[174:177], v[34:37]
	v_mfma_f32_16x16x32_bf16 v[38:41], v[142:145], v[174:177], v[38:41]
	v_mfma_f32_16x16x32_bf16 v[22:25], v[142:145], v[182:185], v[22:25]
	v_mfma_f32_16x16x32_bf16 v[18:21], v[150:153], v[182:185], v[18:21]
	v_mfma_f32_16x16x32_bf16 v[2:5], v[150:153], v[190:193], v[2:5]
	v_mfma_f32_16x16x32_bf16 v[6:9], v[142:145], v[190:193], v[6:9]
	s_setprio 0
	s_barrier
	s_add_i32 s84, s84, 2
	s_add_u32 s46, s46, 0x100
	s_addc_u32 s47, s47, 0
	s_add_u32 s80, s80, 0x100
	s_addc_u32 s81, s81, 0
	s_cmp_gt_u32 s84, 29
	s_cbranch_scc0 .LBB0_904
	s_and_b64 vcc, exec, s[16:17]
	s_mov_b32 s50, 0x90000
	s_mov_b32 s51, 0xa0000
	s_mov_b32 s82, 0xb0000
	s_cbranch_vccz .LBB0_907
	s_barrier
